# attn loop: hoist KV prefetch + V-frag prefetch; FFN-up L0/L1 GEMM: unpadded XOR-swizzled LDS tiles (conflict-free ds_read_b128)
# speedup vs baseline: 1.0143x; 1.0143x over previous
.LBB0_225:
	s_and_b32 s15, s39, 1
	s_mul_i32 s42, s15, 0x2400
	v_add_u32_e32 v64, s42, v87
	ds_read_b128 v[90:93], v64
	ds_read_b128 v[94:97], v64 offset:64
	ds_read_b128 v[102:105], v64 offset:2304
	ds_read_b128 v[106:109], v64 offset:2368
	ds_read_b128 v[114:117], v64 offset:4608
	ds_read_b128 v[118:121], v64 offset:4672
	ds_read_b128 v[126:129], v64 offset:6912
	ds_read_b128 v[130:133], v64 offset:6976
	global_load_dwordx4 v[140:143], v[84:85], off
	global_load_dwordx4 v[144:147], v[82:83], off
	s_waitcnt vmcnt(5) lgkmcnt(7)
	v_mfma_f32_16x16x32_bf16 v[98:101], v[90:93], v[46:49], v[2:5]
	v_add_u32_e32 v64, v64, v88
	v_add_u32_e32 v138, 0x4800, v64
	s_lshl_b32 s15, s15, 6
	s_waitcnt vmcnt(3)
	v_mfma_f32_16x16x32_bf16 v[90:93], v[90:93], v[34:37], v[2:5]
	s_xor_b32 s15, s15, 64
	s_add_i32 s39, s39, 1
	s_mulk_i32 s15, 0x90
	s_waitcnt lgkmcnt(6)
	v_mfma_f32_16x16x32_bf16 v[98:101], v[94:97], v[42:45], v[98:101]
	s_cmp_eq_u32 s0, s39
	s_waitcnt lgkmcnt(5)
	v_mfma_f32_16x16x32_bf16 v[110:113], v[102:105], v[46:49], v[2:5]
	v_mfma_f32_16x16x32_bf16 v[102:105], v[102:105], v[34:37], v[2:5]
	s_nop 3
	v_exp_f32_e32 v98, v98
	v_exp_f32_e32 v99, v99
	v_exp_f32_e32 v100, v100
	s_waitcnt lgkmcnt(3)
	v_mfma_f32_16x16x32_bf16 v[122:125], v[114:117], v[46:49], v[2:5]
	v_exp_f32_e32 v101, v101
	s_waitcnt lgkmcnt(1)
	v_mfma_f32_16x16x32_bf16 v[134:137], v[126:129], v[46:49], v[2:5]
	v_mfma_f32_16x16x32_bf16 v[126:129], v[126:129], v[34:37], v[2:5]
	s_waitcnt vmcnt(2)
	v_mfma_f32_16x16x32_bf16 v[90:93], v[94:97], v[30:33], v[90:93]
	v_mfma_f32_16x16x32_bf16 v[94:97], v[106:109], v[42:45], v[110:113]
	v_mfma_f32_16x16x32_bf16 v[102:105], v[106:109], v[30:33], v[102:105]
	v_mfma_f32_16x16x32_bf16 v[114:117], v[114:117], v[34:37], v[2:5]
	s_nop 5
	v_exp_f32_e32 v94, v94
	v_exp_f32_e32 v95, v95
	v_exp_f32_e32 v96, v96
	v_mfma_f32_16x16x32_bf16 v[106:109], v[118:121], v[42:45], v[122:125]
	v_exp_f32_e32 v97, v97
	v_exp_f32_e32 v102, v102
	v_exp_f32_e32 v103, v103
	s_waitcnt lgkmcnt(0)
	v_mfma_f32_16x16x32_bf16 v[122:125], v[130:133], v[30:33], v[126:129]
	v_exp_f32_e32 v104, v104
	v_exp_f32_e32 v105, v105
	s_nop 0
	v_exp_f32_e32 v126, v90
	v_exp_f32_e32 v127, v91
	v_cvt_pk_bf16_f32 v90, v98, v99
	v_cvt_pk_bf16_f32 v91, v100, v101
	ds_read2_b64 v[98:101], v138 offset1:4
	v_exp_f32_e32 v128, v92
	v_exp_f32_e32 v129, v93
	v_mfma_f32_16x16x32_bf16 v[110:113], v[118:121], v[30:33], v[114:117]
	v_cvt_pk_bf16_f32 v92, v94, v95
	v_cvt_pk_bf16_f32 v93, v96, v97
	v_cvt_pk_bf16_f32 v94, v126, v127
	v_mfma_f32_16x16x32_bf16 v[118:121], v[130:133], v[42:45], v[134:137]
	v_cvt_pk_bf16_f32 v95, v128, v129
	v_cvt_pk_bf16_f32 v96, v102, v103
	v_cvt_pk_bf16_f32 v97, v104, v105
	v_add_u32_e32 v134, 0x5000, v64
	v_add_u32_e32 v135, 0x5800, v64
	v_add_u32_e32 v64, 0x6000, v64
	ds_read2_b64 v[102:105], v134 offset0:32 offset1:36
	ds_read2_b64 v[126:129], v135 offset0:64 offset1:68
	ds_read2_b64 v[130:133], v64 offset0:96 offset1:100
	ds_read2_b64 v[148:151], v138 offset0:8 offset1:12
	ds_read2_b64 v[152:155], v134 offset0:40 offset1:44
	ds_read2_b64 v[156:159], v135 offset0:72 offset1:76
	ds_read2_b64 v[160:163], v64 offset0:104 offset1:108
	v_mov_b64_e32 v[116:117], s[6:7]
	v_mov_b64_e32 v[114:115], s[4:5]
	s_waitcnt lgkmcnt(6)
	v_mfma_f32_16x16x32_bf16 v[22:25], v[102:105], v[90:93], v[22:25]
	v_mfma_f32_16x16x32_bf16 v[18:21], v[102:105], v[94:97], v[18:21]
	v_exp_f32_e32 v102, v120
	v_exp_f32_e32 v103, v121
	v_exp_f32_e32 v104, v110
	v_exp_f32_e32 v105, v111
	v_mfma_f32_16x16x32_bf16 v[50:53], v[98:101], v[90:93], v[50:53]
	v_exp_f32_e32 v110, v122
	v_exp_f32_e32 v111, v123
	v_mfma_f32_16x16x32_bf16 v[38:41], v[98:101], v[94:97], v[38:41]
	v_exp_f32_e32 v98, v106
	v_exp_f32_e32 v99, v107
	v_exp_f32_e32 v100, v108
	v_exp_f32_e32 v101, v109
	v_exp_f32_e32 v106, v118
	v_exp_f32_e32 v107, v119
	v_exp_f32_e32 v108, v112
	v_exp_f32_e32 v109, v113
	v_mfma_f32_16x16x32_bf16 v[58:61], v[114:117], v[90:93], v[58:61]
	v_exp_f32_e32 v112, v124
	v_exp_f32_e32 v113, v125
	v_mfma_f32_16x16x32_bf16 v[54:57], v[114:117], v[94:97], v[54:57]
	s_waitcnt lgkmcnt(5)
	v_mfma_f32_16x16x32_bf16 v[6:9], v[126:129], v[90:93], v[6:9]
	v_mfma_f32_16x16x32_bf16 v[26:29], v[126:129], v[94:97], v[26:29]
	s_waitcnt lgkmcnt(4)
	v_mfma_f32_16x16x32_bf16 v[14:17], v[130:133], v[90:93], v[14:17]
	v_cvt_pk_bf16_f32 v93, v102, v103
	v_cvt_pk_bf16_f32 v92, v106, v107
	v_cvt_pk_bf16_f32 v90, v98, v99
	v_mfma_f32_16x16x32_bf16 v[10:13], v[130:133], v[94:97], v[10:13]
	v_cvt_pk_bf16_f32 v94, v104, v105
	v_cvt_pk_bf16_f32 v95, v108, v109
	v_cvt_pk_bf16_f32 v91, v100, v101
	v_cvt_pk_bf16_f32 v96, v110, v111
	v_cvt_pk_bf16_f32 v97, v112, v113
	s_waitcnt lgkmcnt(3)
	v_mfma_f32_16x16x32_bf16 v[50:53], v[148:151], v[90:93], v[50:53]
	v_lshl_add_u64 v[84:85], v[84:85], 0, s[8:9]
	v_lshl_add_u64 v[82:83], v[82:83], 0, s[12:13]
	v_mfma_f32_16x16x32_bf16 v[38:41], v[148:151], v[94:97], v[38:41]
	s_waitcnt lgkmcnt(2)
	v_mfma_f32_16x16x32_bf16 v[22:25], v[152:155], v[90:93], v[22:25]
	v_mfma_f32_16x16x32_bf16 v[18:21], v[152:155], v[94:97], v[18:21]
	s_waitcnt lgkmcnt(1)
	v_mfma_f32_16x16x32_bf16 v[6:9], v[156:159], v[90:93], v[6:9]
	v_mfma_f32_16x16x32_bf16 v[26:29], v[156:159], v[94:97], v[26:29]
	v_add_u32_e32 v64, s15, v1
	s_waitcnt vmcnt(1)
	ds_write_b128 v64, v[140:143]
	s_waitcnt vmcnt(0)
	ds_write_b128 v64, v[144:147] offset:18432
	s_waitcnt lgkmcnt(2)
	v_mfma_f32_16x16x32_bf16 v[14:17], v[160:163], v[90:93], v[14:17]
	v_mfma_f32_16x16x32_bf16 v[10:13], v[160:163], v[94:97], v[10:13]
	v_mfma_f32_16x16x32_bf16 v[58:61], v[114:117], v[90:93], v[58:61]
	s_waitcnt lgkmcnt(0)
	s_barrier
	v_mfma_f32_16x16x32_bf16 v[54:57], v[114:117], v[94:97], v[54:57]
	s_cbranch_scc0 .LBB0_225
	s_bitcmp1_b32 s0, 0
	s_cselect_b32 s0, 0x2400, 0
	v_add_u32_e32 v64, s0, v87
	ds_read_b128 v[82:85], v64
	ds_read_b128 v[90:93], v64 offset:64
	ds_read_b128 v[98:101], v64 offset:2304
	ds_read_b128 v[102:105], v64 offset:2368
	ds_read_b128 v[110:113], v64 offset:4608
	ds_read_b128 v[114:117], v64 offset:4672
	ds_read_b128 v[122:125], v64 offset:6912
	ds_read_b128 v[126:129], v64 offset:6976
	s_waitcnt lgkmcnt(7)
	v_mfma_f32_16x16x32_bf16 v[94:97], v[82:85], v[46:49], v[2:5]
	s_lshl_b32 s0, s14, 1
	s_add_i32 s17, s17, s16
	s_cmpk_gt_u32 s17, 0x20f
	s_waitcnt lgkmcnt(5)
	v_mfma_f32_16x16x32_bf16 v[106:109], v[98:101], v[46:49], v[2:5]
	s_waitcnt lgkmcnt(3)
	v_mfma_f32_16x16x32_bf16 v[118:121], v[110:113], v[46:49], v[2:5]
	v_mfma_f32_16x16x32_bf16 v[94:97], v[90:93], v[42:45], v[94:97]
	s_waitcnt lgkmcnt(1)
	v_mfma_f32_16x16x32_bf16 v[46:49], v[122:125], v[46:49], v[2:5]
	v_mfma_f32_16x16x32_bf16 v[106:109], v[102:105], v[42:45], v[106:109]
	s_nop 4
	v_exp_f32_e32 v130, v94
	v_exp_f32_e32 v131, v95
	v_exp_f32_e32 v132, v96
	v_exp_f32_e32 v133, v97
	v_mfma_f32_16x16x32_bf16 v[94:97], v[114:117], v[42:45], v[118:121]
	v_exp_f32_e32 v106, v106
	v_exp_f32_e32 v107, v107
	v_exp_f32_e32 v108, v108
	s_waitcnt lgkmcnt(0)
	v_mfma_f32_16x16x32_bf16 v[42:45], v[126:129], v[42:45], v[46:49]
	v_exp_f32_e32 v109, v109
	s_nop 1
	v_exp_f32_e32 v94, v94
	v_exp_f32_e32 v95, v95
	v_mfma_f32_16x16x32_bf16 v[46:49], v[82:85], v[34:37], v[2:5]
	v_exp_f32_e32 v96, v96
	v_exp_f32_e32 v97, v97
	v_cvt_pk_bf16_f32 v82, v94, v95
	v_mfma_f32_16x16x32_bf16 v[46:49], v[90:93], v[30:33], v[46:49]
	v_exp_f32_e32 v118, v42
	v_cvt_pk_bf16_f32 v83, v96, v97
	v_exp_f32_e32 v119, v43
	v_mfma_f32_16x16x32_bf16 v[90:93], v[98:101], v[34:37], v[2:5]
	v_exp_f32_e32 v120, v44
	s_nop 2
	v_exp_f32_e32 v98, v46
	v_exp_f32_e32 v99, v47
	v_mfma_f32_16x16x32_bf16 v[90:93], v[102:105], v[30:33], v[90:93]
	v_exp_f32_e32 v100, v48
	v_exp_f32_e32 v101, v49
	v_exp_f32_e32 v85, v45
	v_mfma_f32_16x16x32_bf16 v[94:97], v[110:113], v[34:37], v[2:5]
	v_cvt_pk_bf16_f32 v42, v130, v131
	s_nop 2
	v_exp_f32_e32 v102, v90
	v_exp_f32_e32 v103, v91
	v_mfma_f32_16x16x32_bf16 v[34:37], v[122:125], v[34:37], v[2:5]
	v_cvt_pk_bf16_f32 v43, v132, v133
	v_cvt_pk_bf16_f32 v44, v106, v107
	v_cvt_pk_bf16_f32 v45, v108, v109
	v_mfma_f32_16x16x32_bf16 v[46:49], v[114:117], v[30:33], v[94:97]
	v_cvt_pk_bf16_f32 v84, v118, v119
	v_cvt_pk_bf16_f32 v85, v120, v85
	s_nop 0
	v_exp_f32_e32 v94, v92
	v_exp_f32_e32 v95, v93
	v_mov_b64_e32 v[92:93], s[6:7]
	v_mov_b64_e32 v[90:91], s[4:5]
	v_mfma_f32_16x16x32_bf16 v[30:33], v[126:129], v[30:33], v[34:37]
	v_exp_f32_e32 v96, v46
	v_exp_f32_e32 v97, v47
	v_exp_f32_e32 v104, v48
	v_exp_f32_e32 v105, v49
	v_cvt_pk_bf16_f32 v34, v98, v99
	s_nop 2
	v_exp_f32_e32 v106, v30
	v_exp_f32_e32 v107, v31
	v_mfma_f32_16x16x32_bf16 v[46:49], v[90:93], v[42:45], v[58:61]
	v_cvt_pk_bf16_f32 v35, v100, v101
	v_cvt_pk_bf16_f32 v36, v102, v103
	v_cvt_pk_bf16_f32 v37, v94, v95
	v_exp_f32_e32 v58, v32
	v_exp_f32_e32 v33, v33
	v_mfma_f32_16x16x32_bf16 v[54:57], v[90:93], v[34:37], v[54:57]
	v_cvt_pk_bf16_f32 v30, v96, v97
	v_cvt_pk_bf16_f32 v31, v104, v105
	v_cvt_pk_bf16_f32 v32, v106, v107
	v_mfma_f32_16x16x32_bf16 v[46:49], v[90:93], v[82:85], v[46:49]
	v_cvt_pk_bf16_f32 v33, v58, v33
	s_nop 1
	v_mfma_f32_16x16x32_bf16 v[54:57], v[90:93], v[30:33], v[54:57]
	s_nop 3
	v_add_u32_e32 v47, v64, v88
	s_nop 2
	v_add_u32_e32 v55, 0x4800, v47
	ds_read2_b64 v[56:59], v55 offset1:4
	ds_read2_b64 v[90:93], v55 offset0:8 offset1:12
	s_waitcnt lgkmcnt(1)
	v_mfma_f32_16x16x32_bf16 v[48:51], v[56:59], v[42:45], v[50:53]
	s_nop 2
	v_add_u32_e32 v52, 0x5000, v47
	v_mfma_f32_16x16x32_bf16 v[38:41], v[56:59], v[34:37], v[38:41]
	ds_read2_b64 v[56:59], v52 offset0:32 offset1:36
	ds_read2_b64 v[94:97], v52 offset0:40 offset1:44
	v_add_u32_e32 v52, 0x5800, v47
	v_add_u32_e32 v47, 0x6000, v47
	s_waitcnt lgkmcnt(2)
	v_mfma_f32_16x16x32_bf16 v[48:51], v[90:93], v[82:85], v[48:51]
	ds_read2_b64 v[98:101], v52 offset0:64 offset1:68
	ds_read2_b64 v[102:105], v52 offset0:72 offset1:76
	v_lshl_add_u64 v[52:53], v[72:73], 0, s[0:1]
	v_mfma_f32_16x16x32_bf16 v[38:41], v[90:93], v[30:33], v[38:41]
	ds_read2_b64 v[90:93], v47 offset0:96 offset1:100
	ds_read2_b64 v[106:109], v47 offset0:104 offset1:108
	v_div_scale_f32 v47, s[42:43], v46, v46, 1.0
	v_rcp_f32_e32 v55, v47
	s_waitcnt lgkmcnt(5)
	v_mfma_f32_16x16x32_bf16 v[22:25], v[56:59], v[42:45], v[22:25]
	s_waitcnt lgkmcnt(0)
	s_barrier
	v_mfma_f32_16x16x32_bf16 v[18:21], v[56:59], v[34:37], v[18:21]
	v_fma_f32 v56, -v47, v55, 1.0
	v_fmac_f32_e32 v55, v56, v55
	v_div_scale_f32 v56, vcc, 1.0, v46, 1.0
	v_mfma_f32_16x16x32_bf16 v[6:9], v[98:101], v[42:45], v[6:9]
	v_mul_f32_e32 v57, v56, v55
	v_fma_f32 v58, -v47, v57, v56
	v_fmac_f32_e32 v57, v58, v55
	v_mfma_f32_16x16x32_bf16 v[14:17], v[90:93], v[42:45], v[14:17]
	v_fma_f32 v47, -v47, v57, v56
	v_div_fmas_f32 v47, v47, v55, v57
	v_div_fixup_f32 v46, v47, v46, 1.0
	v_mfma_f32_16x16x32_bf16 v[22:25], v[94:97], v[82:85], v[22:25]
	v_lshl_add_u64 v[56:57], v[52:53], 0, v[80:81]
	v_pk_mul_f32 v[50:51], v[46:47], v[50:51] op_sel_hi:[0,1]
	v_pk_mul_f32 v[48:49], v[46:47], v[48:49] op_sel_hi:[0,1]
	v_mfma_f32_16x16x32_bf16 v[6:9], v[102:105], v[82:85], v[6:9]
	v_cvt_pk_bf16_f32 v48, v48, v49
	s_nop 2
	v_pk_mul_f32 v[24:25], v[46:47], v[24:25] op_sel_hi:[0,1]
	v_pk_mul_f32 v[22:23], v[46:47], v[22:23] op_sel_hi:[0,1]
	v_mfma_f32_16x16x32_bf16 v[10:13], v[90:93], v[34:37], v[10:13]
	v_cvt_pk_bf16_f32 v22, v22, v23
	v_cvt_pk_bf16_f32 v23, v24, v25
	v_pk_mul_f32 v[8:9], v[46:47], v[8:9] op_sel_hi:[0,1]
	v_mfma_f32_16x16x32_bf16 v[14:17], v[106:109], v[82:85], v[14:17]
	v_mul_f32_e64 v6, v46, v6
	v_mul_f32_e64 v7, v46, v7
	global_store_dwordx2 v[56:57], v[22:23], off offset:32
	v_cvt_pk_bf16_f32 v22, v6, v7
	v_cvt_pk_bf16_f32 v23, v8, v9
	v_mfma_f32_16x16x32_bf16 v[6:9], v[106:109], v[30:33], v[10:13]
	v_cvt_pk_bf16_f32 v49, v50, v51
	global_store_dwordx2 v[56:57], v[48:49], off
	global_store_dwordx2 v[56:57], v[22:23], off offset:64
	v_pk_mul_f32 v[12:13], v[46:47], v[14:15] op_sel_hi:[0,1]
	v_div_scale_f32 v14, s[14:15], v54, v54, 1.0
	v_rcp_f32_e32 v15, v14
	v_pk_mul_f32 v[10:11], v[46:47], v[16:17] op_sel_hi:[0,1]
	v_cvt_pk_bf16_f32 v12, v12, v13
	v_cvt_pk_bf16_f32 v13, v10, v11
	v_fma_f32 v10, -v14, v15, 1.0
	v_fmac_f32_e32 v15, v10, v15
	v_div_scale_f32 v10, vcc, 1.0, v54, 1.0
	v_mul_f32_e32 v11, v10, v15
	global_store_dwordx2 v[56:57], v[12:13], off offset:96
	v_fma_f32 v12, -v14, v11, v10
	v_mfma_f32_16x16x32_bf16 v[26:29], v[98:101], v[34:37], v[26:29]
	v_fmac_f32_e32 v11, v12, v15
	v_fma_f32 v10, -v14, v11, v10
	v_div_fmas_f32 v10, v10, v15, v11
	v_mfma_f32_16x16x32_bf16 v[18:21], v[94:97], v[30:33], v[18:21]
	v_div_fixup_f32 v10, v10, v54, 1.0
	v_pk_mul_f32 v[14:15], v[10:11], v[40:41] op_sel_hi:[0,1]
	v_pk_mul_f32 v[16:17], v[10:11], v[38:39] op_sel_hi:[0,1]
	v_mfma_f32_16x16x32_bf16 v[26:29], v[102:105], v[30:33], v[26:29]
	v_lshl_add_u64 v[12:13], v[52:53], 0, v[78:79]
	v_cvt_pk_bf16_f32 v16, v16, v17
	v_cvt_pk_bf16_f32 v17, v14, v15
	global_store_dwordx2 v[12:13], v[16:17], off
	v_pk_mul_f32 v[14:15], v[10:11], v[20:21] op_sel_hi:[0,1]
	v_pk_mul_f32 v[16:17], v[10:11], v[18:19] op_sel_hi:[0,1]
	v_cvt_pk_bf16_f32 v16, v16, v17
	v_cvt_pk_bf16_f32 v17, v14, v15
	global_store_dwordx2 v[12:13], v[16:17], off offset:32
	v_pk_mul_f32 v[14:15], v[10:11], v[28:29] op_sel_hi:[0,1]
	v_pk_mul_f32 v[16:17], v[10:11], v[26:27] op_sel_hi:[0,1]
	v_pk_mul_f32 v[8:9], v[10:11], v[8:9] op_sel_hi:[0,1]
	v_pk_mul_f32 v[6:7], v[10:11], v[6:7] op_sel_hi:[0,1]
	v_cvt_pk_bf16_f32 v16, v16, v17
	v_cvt_pk_bf16_f32 v17, v14, v15
	v_cvt_pk_bf16_f32 v6, v6, v7
	v_cvt_pk_bf16_f32 v7, v8, v9
	global_store_dwordx2 v[12:13], v[16:17], off offset:64
	global_store_dwordx2 v[12:13], v[6:7], off offset:96
	s_cbranch_scc0 .LBB0_220

.LBB0_352:
	v_mov_b32_e32 v3, v2
	s_cmpk_gt_u32 s2, 0x16af
	s_cbranch_scc1 .LBB0_357
	v_lshlrev_b32_e32 v4, 4, v2
	v_and_b32_e32 v130, 0x70, v4
	v_mov_b32_e32 v131, 0
	v_lshl_add_u64 v[4:5], s[86:87], 0, v[130:131]
	s_mov_b64 s[0:1], 0x4450000
	v_lshrrev_b32_e32 v1, 3, v2
	v_lshl_add_u64 v[132:133], v[4:5], 0, s[0:1]
	s_mov_b64 s[0:1], 0x500000
	v_lshl_add_u64 v[134:135], v[4:5], 0, s[0:1]
	v_mul_u32_u24_e32 v4, 0x48, v1
	v_lshlrev_b32_e32 v4, 1, v4
	s_add_i32 s0, 0, 0x12000
	v_add3_u32 v144, 0, v4, v130
	v_add3_u32 v145, s0, v4, v130
	v_and_b32_e32 v4, 15, v2
	v_lshrrev_b32_e32 v5, 1, v2
	s_movk_i32 s1, 0x180
	v_and_or_b32 v4, v5, s1, v4
	v_mul_u32_u24_e32 v4, 0x90, v4
	v_and_b32_e32 v5, 48, v2
	v_add3_u32 v146, 0, v4, v5
	v_and_b32_e32 v4, 0xcf, v2
	v_mul_u32_u24_e32 v4, 0x90, v4
	v_add3_u32 v147, s0, v4, v5
	v_lshrrev_b32_e32 v4, 1, v1
	v_and_b32_e32 v4, 7, v4
	v_and_b32_e32 v5, 7, v2
	v_xor_b32_e32 v4, v4, v5
	v_lshlrev_b32_e32 v4, 4, v4
	v_lshl_add_u32 v144, v1, 7, v4
	v_add_u32_e32 v145, 0x10000, v144
	v_and_b32_e32 v4, 15, v2
	v_lshrrev_b32_e32 v5, 1, v4
	v_bfe_u32 v216, v2, 4, 2
	v_xor_b32_e32 v5, v5, v216
	v_lshlrev_b32_e32 v5, 4, v5
	v_lshrrev_b32_e32 v216, 8, v2
	v_lshl_add_u32 v216, v216, 7, v4
	v_lshl_add_u32 v146, v216, 7, v5
	v_xor_b32_e32 v216, 64, v146
	v_bfe_u32 v217, v2, 6, 2
	v_lshl_add_u32 v217, v217, 6, v4
	v_lshl_add_u32 v147, v217, 7, v5
	v_add_u32_e32 v147, 0x10000, v147
	v_xor_b32_e32 v217, 64, v147
	v_ashrrev_i32_e32 v4, 1, v3
	v_and_b32_e32 v148, 0xc0, v3
	v_and_b32_e32 v5, 15, v3
	v_lshrrev_b32_e32 v3, 1, v3
	s_and_b32 s6, s2, 7
	s_movk_i32 s0, 0xff80
	v_and_b32_e32 v130, 24, v3
	v_and_b32_e32 v2, 7, v2
	s_lshr_b32 s3, s2, 3
	s_mul_i32 s6, s6, 33
	v_and_or_b32 v149, v4, s0, v5
	v_lshl_add_u64 v[4:5], s[86:87], 0, v[130:131]
	s_mov_b64 s[0:1], 0x21250000
	v_lshlrev_b32_e32 v130, 4, v2
	v_lshl_add_u64 v[136:137], v[4:5], 0, s[0:1]
	s_ashr_i32 s7, s33, 3
	v_lshl_add_u64 v[138:139], s[86:87], 0, v[130:131]
	s_add_i32 s8, s3, s6
	s_mov_b32 s9, 0x20000
	s_mov_b32 s10, 0x40000
	s_mov_b32 s11, 0x60000
	s_mov_b32 s12, 0x4450000
	s_mov_b32 s13, 0x4470000
	s_mov_b32 s14, 0x4490000
	s_mov_b32 s15, 0x44b0000
	s_waitcnt lgkmcnt(0)
	s_mov_b32 s16, 0x500000
	s_mov_b32 s17, 0x520000
	s_mov_b32 s28, 0x540000
	s_mov_b32 s29, 0x560000
	s_movk_i32 s36, 0x1600
.LBB0_354:
	s_mul_hi_i32 s0, s3, 0x2e8ba2e9
	s_lshr_b32 s1, s0, 31
	s_ashr_i32 s0, s0, 4
	s_add_i32 s40, s0, s1
	s_lshl_b32 s0, s40, 2
	s_sub_i32 s1, 33, s0
	s_min_u32 s1, s1, 4
	v_cvt_f32_ubyte0_e32 v2, s1
	v_rcp_iflag_f32_e32 v2, v2
	s_sub_i32 s41, 0, s1
	s_mul_i32 s37, s40, 0xffffffa8
	s_add_i32 s37, s37, s3
	v_mul_f32_e32 v2, 0x4f7ffffe, v2
	v_cvt_u32_f32_e32 v2, v2
	s_abs_i32 s39, s37
	s_ashr_i32 s38, s37, 31
	s_mulk_i32 s40, 0x54
	v_readfirstlane_b32 s42, v2
	s_mul_i32 s41, s41, s42
	s_mul_hi_u32 s41, s42, s41
	s_add_i32 s42, s42, s41
	s_mul_hi_u32 s41, s39, s42
	s_mul_i32 s42, s41, s1
	s_sub_i32 s39, s39, s42
	s_add_i32 s42, s41, 1
	s_sub_i32 s43, s39, s1
	s_cmp_ge_u32 s39, s1
	s_cselect_b32 s41, s42, s41
	s_cselect_b32 s39, s43, s39
	s_add_i32 s42, s41, 1
	s_cmp_ge_u32 s39, s1
	s_cselect_b32 s39, s42, s41
	s_xor_b32 s39, s39, s38
	s_sub_i32 s38, s39, s38
	s_add_i32 s0, s0, s6
	s_mul_i32 s41, s1, s38
	s_add_i32 s0, s0, s37
	s_sub_i32 s0, s0, s41
	s_lshl_b32 s37, s0, 8
	v_or_b32_e32 v2, s37, v1
	v_ashrrev_i32_e32 v3, 31, v2
	v_lshlrev_b64 v[2:3], 11, v[2:3]
	v_lshl_add_u64 v[2:3], v[132:133], 0, v[2:3]
	v_add_co_u32_e32 v6, vcc, s9, v2
	s_lshl_b32 s38, s38, 8
	s_nop 0
	v_addc_co_u32_e32 v7, vcc, 0, v3, vcc
	v_or_b32_e32 v4, s38, v1
	global_load_dwordx4 v[20:23], v[2:3], off
	global_load_dwordx4 v[24:27], v[6:7], off
	v_add_co_u32_e32 v6, vcc, s10, v2
	v_ashrrev_i32_e32 v5, 31, v4
	s_nop 0
	v_addc_co_u32_e32 v7, vcc, 0, v3, vcc
	v_lshlrev_b64 v[52:53], 11, v[4:5]
	v_add_co_u32_e32 v2, vcc, s11, v2
	v_lshl_add_u64 v[4:5], v[134:135], 0, v[52:53]
	s_nop 0
	v_addc_co_u32_e32 v3, vcc, 0, v3, vcc
	global_load_dwordx4 v[28:31], v[6:7], off
	global_load_dwordx4 v[32:35], v[2:3], off
	v_add_co_u32_e32 v2, vcc, s9, v4
	s_waitcnt vmcnt(63) expcnt(7) lgkmcnt(15)
	s_nop 0
	v_addc_co_u32_e32 v3, vcc, 0, v5, vcc
	s_barrier
	global_load_dwordx4 v[36:39], v[4:5], off
	global_load_dwordx4 v[40:43], v[2:3], off
	v_add_co_u32_e32 v2, vcc, s10, v4
	s_sub_i32 s41, s8, s41
	s_nop 0
	v_addc_co_u32_e32 v3, vcc, 0, v5, vcc
	v_add_co_u32_e32 v4, vcc, s11, v4
	s_sub_i32 s40, s41, s40
	s_nop 0
	v_addc_co_u32_e32 v5, vcc, 0, v5, vcc
	global_load_dwordx4 v[44:47], v[2:3], off
	global_load_dwordx4 v[48:51], v[4:5], off
	v_lshl_add_u32 v54, s40, 8, v1
	v_ashrrev_i32_e32 v55, 31, v54
	v_lshl_add_u64 v[140:141], v[138:139], 0, v[52:53]
	v_lshlrev_b64 v[52:53], 11, v[54:55]
	s_mov_b64 s[0:1], 0
	s_mov_b32 s39, 0
	v_mov_b32_e32 v2, 0
	v_mov_b32_e32 v3, v131
	v_mov_b32_e32 v4, v131
	v_mov_b32_e32 v5, v131
	v_mov_b32_e32 v6, 0
	v_mov_b32_e32 v7, v131
	v_mov_b32_e32 v8, v131
	v_mov_b32_e32 v9, v131
	v_mov_b32_e32 v10, 0
	v_mov_b32_e32 v11, v131
	v_mov_b32_e32 v12, v131
	v_mov_b32_e32 v13, v131
	v_mov_b32_e32 v14, 0
	v_mov_b32_e32 v15, v131
	v_mov_b32_e32 v16, v131
	v_mov_b32_e32 v17, v131
	v_mov_b32_e32 v18, 0
	v_lshl_add_u64 v[142:143], v[138:139], 0, v[52:53]
	v_mov_b32_e32 v19, v131
	v_mov_b32_e32 v52, v131
	v_mov_b32_e32 v53, v131
	v_mov_b32_e32 v54, 0
	v_mov_b32_e32 v55, v131
	v_mov_b32_e32 v56, v131
	v_mov_b32_e32 v57, v131
	v_mov_b32_e32 v58, 0
	v_mov_b32_e32 v59, v131
	v_mov_b32_e32 v60, v131
	v_mov_b32_e32 v61, v131
	v_mov_b32_e32 v62, 0
	v_mov_b32_e32 v63, v131
	v_mov_b32_e32 v64, v131
	v_mov_b32_e32 v65, v131
	v_mov_b32_e32 v66, 0
	v_mov_b32_e32 v67, v131
	v_mov_b32_e32 v68, v131
	v_mov_b32_e32 v69, v131
	v_mov_b32_e32 v70, 0
	v_mov_b32_e32 v71, v131
	v_mov_b32_e32 v72, v131
	v_mov_b32_e32 v73, v131
	v_mov_b32_e32 v74, 0
	s_waitcnt vmcnt(7)
	ds_write_b128 v144, v[20:23]
	s_waitcnt vmcnt(6)
	ds_write_b128 v144, v[24:27] offset:8192
	s_waitcnt vmcnt(5)
	ds_write_b128 v144, v[28:31] offset:16384
	s_waitcnt vmcnt(4)
	ds_write_b128 v144, v[32:35] offset:24576
	s_waitcnt vmcnt(3)
	ds_write_b128 v145, v[36:39]
	s_waitcnt vmcnt(2)
	ds_write_b128 v145, v[40:43] offset:8192
	s_waitcnt vmcnt(1)
	ds_write_b128 v145, v[44:47] offset:16384
	s_waitcnt vmcnt(0)
	ds_write_b128 v145, v[48:51] offset:24576
	v_mov_b32_e32 v20, v131
	v_mov_b32_e32 v21, v131
	v_mov_b32_e32 v22, 0
	v_mov_b32_e32 v23, v131
	v_mov_b32_e32 v24, v131
	v_mov_b32_e32 v25, v131
	v_mov_b32_e32 v26, 0
	v_mov_b32_e32 v27, v131
	v_mov_b32_e32 v28, v131
	v_mov_b32_e32 v29, v131
	v_mov_b32_e32 v30, 0
	v_mov_b32_e32 v31, v131
	v_mov_b32_e32 v32, v131
	v_mov_b32_e32 v33, v131
	v_mov_b32_e32 v34, 0
	v_mov_b32_e32 v35, v131
	v_mov_b32_e32 v36, v131
	v_mov_b32_e32 v37, v131
	v_mov_b32_e32 v38, 0
	v_mov_b32_e32 v39, v131
	v_mov_b32_e32 v40, v131
	v_mov_b32_e32 v41, v131
	v_mov_b32_e32 v42, 0
	v_mov_b32_e32 v43, v131
	v_mov_b32_e32 v44, v131
	v_mov_b32_e32 v45, v131
	v_mov_b32_e32 v46, 0
	v_mov_b32_e32 v47, v131
	v_mov_b32_e32 v48, v131
	v_mov_b32_e32 v49, v131
	v_mov_b32_e32 v50, 0
	v_mov_b32_e32 v51, v131
	v_mov_b32_e32 v75, v131
	v_mov_b32_e32 v76, v131
	v_mov_b32_e32 v77, v131
	v_mov_b32_e32 v78, 0
	v_mov_b32_e32 v79, v131
	v_mov_b32_e32 v80, v131
	v_mov_b32_e32 v81, v131
	v_mov_b32_e32 v82, 0
	v_mov_b32_e32 v83, v131
	v_mov_b32_e32 v84, v131
	v_mov_b32_e32 v85, v131
	v_mov_b32_e32 v86, 0
	v_mov_b32_e32 v87, v131
	v_mov_b32_e32 v88, v131
	v_mov_b32_e32 v89, v131
	v_mov_b32_e32 v90, 0
	v_mov_b32_e32 v91, v131
	v_mov_b32_e32 v92, v131
	v_mov_b32_e32 v93, v131
	v_mov_b32_e32 v94, 0
	v_mov_b32_e32 v95, v131
	v_mov_b32_e32 v96, v131
	v_mov_b32_e32 v97, v131
	v_mov_b32_e32 v98, 0
	v_mov_b32_e32 v99, v131
	v_mov_b32_e32 v100, v131
	v_mov_b32_e32 v101, v131
	v_mov_b32_e32 v102, 0
	v_mov_b32_e32 v103, v131
	v_mov_b32_e32 v104, v131
	v_mov_b32_e32 v105, v131
	v_mov_b32_e32 v106, 0
	v_mov_b32_e32 v107, v131
	v_mov_b32_e32 v108, v131
	v_mov_b32_e32 v109, v131
	v_mov_b32_e32 v110, 0
	v_mov_b32_e32 v111, v131
	v_mov_b32_e32 v112, v131
	v_mov_b32_e32 v113, v131
	v_mov_b32_e32 v114, 0
	v_mov_b32_e32 v115, v131
	v_mov_b32_e32 v116, v131
	v_mov_b32_e32 v117, v131
	v_mov_b32_e32 v118, 0
	v_mov_b32_e32 v119, v131
	v_mov_b32_e32 v120, v131
	v_mov_b32_e32 v121, v131
	v_mov_b32_e32 v122, 0
	v_mov_b32_e32 v123, v131
	v_mov_b32_e32 v124, v131
	v_mov_b32_e32 v125, v131
	v_mov_b32_e32 v126, 0
	v_mov_b32_e32 v127, v131
	v_mov_b32_e32 v128, v131
	v_mov_b32_e32 v129, v131
	s_waitcnt lgkmcnt(0)
	s_barrier
.LBB0_355:
	v_lshl_add_u64 v[150:151], v[142:143], 0, s[0:1]
	v_add_co_u32_e32 v152, vcc, s12, v150
	s_and_b32 s40, s39, 1
	s_nop 0
	v_addc_co_u32_e32 v153, vcc, 0, v151, vcc
	v_add_co_u32_e32 v154, vcc, s13, v150
	s_mul_i32 s41, s40, 0x8000
	s_nop 0
	v_addc_co_u32_e32 v155, vcc, 0, v151, vcc
	v_add_co_u32_e32 v158, vcc, s14, v150
	v_add_u32_e32 v198, s41, v147
	v_add_u32_e32 v219, s41, v217
	s_nop 0
	v_addc_co_u32_e32 v159, vcc, 0, v151, vcc
	v_add_co_u32_e32 v162, vcc, s15, v150
	v_add_u32_e32 v130, s41, v146
	v_add_u32_e32 v218, s41, v216
	s_nop 0
	v_addc_co_u32_e32 v163, vcc, 0, v151, vcc
	global_load_dwordx4 v[150:153], v[152:153], off offset:128
	s_nop 0
	global_load_dwordx4 v[154:157], v[154:155], off offset:128
	s_nop 0
	global_load_dwordx4 v[158:161], v[158:159], off offset:128
	s_nop 0
	global_load_dwordx4 v[162:165], v[162:163], off offset:128
	ds_read_b128 v[166:169], v198
	ds_read_b128 v[170:173], v198 offset:2048
	ds_read_b128 v[174:177], v198 offset:4096
	ds_read_b128 v[178:181], v198 offset:6144
	ds_read_b128 v[182:185], v130
	ds_read_b128 v[186:189], v130 offset:2048
	ds_read_b128 v[190:193], v130 offset:4096
	ds_read_b128 v[194:197], v130 offset:6144
	s_add_i32 s39, s39, 1
	s_setprio 1
	s_waitcnt lgkmcnt(3)
	v_mfma_f32_16x16x32_bf16 v[126:129], v[166:169], v[182:185], v[126:129]
	v_mfma_f32_16x16x32_bf16 v[122:125], v[170:173], v[182:185], v[122:125]
	v_mfma_f32_16x16x32_bf16 v[118:121], v[174:177], v[182:185], v[118:121]
	v_mfma_f32_16x16x32_bf16 v[114:117], v[178:181], v[182:185], v[114:117]
	s_waitcnt lgkmcnt(2)
	v_mfma_f32_16x16x32_bf16 v[110:113], v[166:169], v[186:189], v[110:113]
	v_mfma_f32_16x16x32_bf16 v[106:109], v[170:173], v[186:189], v[106:109]
	v_mfma_f32_16x16x32_bf16 v[102:105], v[174:177], v[186:189], v[102:105]
	v_mfma_f32_16x16x32_bf16 v[98:101], v[178:181], v[186:189], v[98:101]
	s_waitcnt lgkmcnt(1)
	v_mfma_f32_16x16x32_bf16 v[94:97], v[166:169], v[190:193], v[94:97]
	v_mfma_f32_16x16x32_bf16 v[90:93], v[170:173], v[190:193], v[90:93]
	v_mfma_f32_16x16x32_bf16 v[86:89], v[174:177], v[190:193], v[86:89]
	v_mfma_f32_16x16x32_bf16 v[82:85], v[178:181], v[190:193], v[82:85]
	s_waitcnt lgkmcnt(0)
	v_mfma_f32_16x16x32_bf16 v[78:81], v[166:169], v[194:197], v[78:81]
	v_mfma_f32_16x16x32_bf16 v[74:77], v[170:173], v[194:197], v[74:77]
	v_mfma_f32_16x16x32_bf16 v[70:73], v[174:177], v[194:197], v[70:73]
	v_mfma_f32_16x16x32_bf16 v[66:69], v[178:181], v[194:197], v[66:69]
	s_setprio 0
	ds_read_b128 v[182:185], v130 offset:8192
	ds_read_b128 v[186:189], v130 offset:10240
	ds_read_b128 v[190:193], v130 offset:12288
	ds_read_b128 v[194:197], v130 offset:14336
	s_setprio 1
	s_waitcnt lgkmcnt(3)
	v_mfma_f32_16x16x32_bf16 v[62:65], v[166:169], v[182:185], v[62:65]
	v_mfma_f32_16x16x32_bf16 v[58:61], v[170:173], v[182:185], v[58:61]
	v_mfma_f32_16x16x32_bf16 v[54:57], v[174:177], v[182:185], v[54:57]
	v_mfma_f32_16x16x32_bf16 v[50:53], v[178:181], v[182:185], v[50:53]
	s_waitcnt lgkmcnt(2)
	v_mfma_f32_16x16x32_bf16 v[46:49], v[166:169], v[186:189], v[46:49]
	v_mfma_f32_16x16x32_bf16 v[42:45], v[170:173], v[186:189], v[42:45]
	v_mfma_f32_16x16x32_bf16 v[38:41], v[174:177], v[186:189], v[38:41]
	v_mfma_f32_16x16x32_bf16 v[34:37], v[178:181], v[186:189], v[34:37]
	s_waitcnt lgkmcnt(1)
	v_mfma_f32_16x16x32_bf16 v[30:33], v[166:169], v[190:193], v[30:33]
	v_mfma_f32_16x16x32_bf16 v[26:29], v[170:173], v[190:193], v[26:29]
	v_mfma_f32_16x16x32_bf16 v[22:25], v[174:177], v[190:193], v[22:25]
	v_mfma_f32_16x16x32_bf16 v[18:21], v[178:181], v[190:193], v[18:21]
	s_waitcnt lgkmcnt(0)
	v_mfma_f32_16x16x32_bf16 v[14:17], v[166:169], v[194:197], v[14:17]
	v_mfma_f32_16x16x32_bf16 v[10:13], v[170:173], v[194:197], v[10:13]
	v_mfma_f32_16x16x32_bf16 v[6:9], v[174:177], v[194:197], v[6:9]
	v_mfma_f32_16x16x32_bf16 v[2:5], v[178:181], v[194:197], v[2:5]
	s_setprio 0
	v_lshl_add_u64 v[174:175], v[140:141], 0, s[0:1]
	v_add_co_u32_e32 v166, vcc, s16, v174
	s_lshl_b32 s40, s40, 8
	s_nop 0
	v_addc_co_u32_e32 v167, vcc, 0, v175, vcc
	v_add_co_u32_e32 v170, vcc, s17, v174
	s_xor_b32 s40, s40, 0x100
	s_nop 0
	v_addc_co_u32_e32 v171, vcc, 0, v175, vcc
	v_add_co_u32_e32 v176, vcc, s28, v174
	global_load_dwordx4 v[166:169], v[166:167], off offset:128
	s_nop 0
	global_load_dwordx4 v[170:173], v[170:171], off offset:128
	v_addc_co_u32_e32 v177, vcc, 0, v175, vcc
	v_add_co_u32_e32 v178, vcc, s29, v174
	s_mulk_i32 s40, 0x80
	s_nop 0
	v_addc_co_u32_e32 v179, vcc, 0, v175, vcc
	global_load_dwordx4 v[174:177], v[176:177], off offset:128
	s_nop 0
	global_load_dwordx4 v[178:181], v[178:179], off offset:128
	v_add_u32_e32 v182, s40, v144
	s_waitcnt vmcnt(7)
	ds_write_b128 v182, v[150:153]
	s_waitcnt vmcnt(6)
	ds_write_b128 v182, v[154:157] offset:8192
	s_waitcnt vmcnt(5)
	ds_write_b128 v182, v[158:161] offset:16384
	s_waitcnt vmcnt(4)
	ds_write_b128 v182, v[162:165] offset:24576
	ds_read_b128 v[150:153], v219
	ds_read_b128 v[154:157], v219 offset:2048
	ds_read_b128 v[158:161], v219 offset:4096
	ds_read_b128 v[162:165], v219 offset:6144
	ds_read_b128 v[182:185], v218
	ds_read_b128 v[186:189], v218 offset:2048
	ds_read_b128 v[190:193], v218 offset:4096
	ds_read_b128 v[194:197], v218 offset:6144
	s_setprio 1
	s_waitcnt lgkmcnt(3)
	v_mfma_f32_16x16x32_bf16 v[126:129], v[150:153], v[182:185], v[126:129]
	v_mfma_f32_16x16x32_bf16 v[122:125], v[154:157], v[182:185], v[122:125]
	v_mfma_f32_16x16x32_bf16 v[118:121], v[158:161], v[182:185], v[118:121]
	v_mfma_f32_16x16x32_bf16 v[114:117], v[162:165], v[182:185], v[114:117]
	s_waitcnt lgkmcnt(2)
	v_mfma_f32_16x16x32_bf16 v[110:113], v[150:153], v[186:189], v[110:113]
	v_mfma_f32_16x16x32_bf16 v[106:109], v[154:157], v[186:189], v[106:109]
	v_mfma_f32_16x16x32_bf16 v[102:105], v[158:161], v[186:189], v[102:105]
	v_mfma_f32_16x16x32_bf16 v[98:101], v[162:165], v[186:189], v[98:101]
	s_waitcnt lgkmcnt(1)
	v_mfma_f32_16x16x32_bf16 v[94:97], v[150:153], v[190:193], v[94:97]
	v_mfma_f32_16x16x32_bf16 v[90:93], v[154:157], v[190:193], v[90:93]
	v_mfma_f32_16x16x32_bf16 v[86:89], v[158:161], v[190:193], v[86:89]
	v_mfma_f32_16x16x32_bf16 v[82:85], v[162:165], v[190:193], v[82:85]
	s_waitcnt lgkmcnt(0)
	v_mfma_f32_16x16x32_bf16 v[78:81], v[150:153], v[194:197], v[78:81]
	v_mfma_f32_16x16x32_bf16 v[74:77], v[154:157], v[194:197], v[74:77]
	v_mfma_f32_16x16x32_bf16 v[70:73], v[158:161], v[194:197], v[70:73]
	v_mfma_f32_16x16x32_bf16 v[66:69], v[162:165], v[194:197], v[66:69]
	s_setprio 0
	ds_read_b128 v[182:185], v218 offset:8192
	ds_read_b128 v[186:189], v218 offset:10240
	ds_read_b128 v[190:193], v218 offset:12288
	ds_read_b128 v[194:197], v218 offset:14336
	s_setprio 1
	s_waitcnt lgkmcnt(3)
	v_mfma_f32_16x16x32_bf16 v[62:65], v[150:153], v[182:185], v[62:65]
	v_mfma_f32_16x16x32_bf16 v[58:61], v[154:157], v[182:185], v[58:61]
	v_mfma_f32_16x16x32_bf16 v[54:57], v[158:161], v[182:185], v[54:57]
	v_mfma_f32_16x16x32_bf16 v[50:53], v[162:165], v[182:185], v[50:53]
	s_waitcnt lgkmcnt(2)
	v_mfma_f32_16x16x32_bf16 v[46:49], v[150:153], v[186:189], v[46:49]
	v_mfma_f32_16x16x32_bf16 v[42:45], v[154:157], v[186:189], v[42:45]
	v_mfma_f32_16x16x32_bf16 v[38:41], v[158:161], v[186:189], v[38:41]
	v_mfma_f32_16x16x32_bf16 v[34:37], v[162:165], v[186:189], v[34:37]
	s_waitcnt lgkmcnt(1)
	v_mfma_f32_16x16x32_bf16 v[30:33], v[150:153], v[190:193], v[30:33]
	v_mfma_f32_16x16x32_bf16 v[26:29], v[154:157], v[190:193], v[26:29]
	v_mfma_f32_16x16x32_bf16 v[22:25], v[158:161], v[190:193], v[22:25]
	v_mfma_f32_16x16x32_bf16 v[18:21], v[162:165], v[190:193], v[18:21]
	s_waitcnt lgkmcnt(0)
	v_mfma_f32_16x16x32_bf16 v[14:17], v[150:153], v[194:197], v[14:17]
	v_mfma_f32_16x16x32_bf16 v[10:13], v[154:157], v[194:197], v[10:13]
	v_mfma_f32_16x16x32_bf16 v[6:9], v[158:161], v[194:197], v[6:9]
	v_mfma_f32_16x16x32_bf16 v[2:5], v[162:165], v[194:197], v[2:5]
	s_setprio 0
	s_add_u32 s0, s0, 0x80
	s_addc_u32 s1, s1, 0
	v_add_u32_e32 v130, s40, v145
	s_cmpk_eq_i32 s0, 0x780
	s_waitcnt vmcnt(3)
	ds_write_b128 v130, v[166:169]
	s_waitcnt vmcnt(2)
	ds_write_b128 v130, v[170:173] offset:8192
	s_waitcnt vmcnt(1)
	ds_write_b128 v130, v[174:177] offset:16384
	s_waitcnt vmcnt(0)
	ds_write_b128 v130, v[178:181] offset:24576
	s_waitcnt lgkmcnt(0)
	s_barrier
	s_cbranch_scc0 .LBB0_355
	ds_read_b128 v[140:143], v147 offset:32768
	ds_read_b128 v[150:153], v147 offset:34816
	ds_read_b128 v[154:157], v147 offset:36864
	ds_read_b128 v[158:161], v147 offset:38912
	ds_read_b128 v[162:165], v146 offset:32768
	ds_read_b128 v[166:169], v146 offset:34816
	ds_read_b128 v[170:173], v146 offset:36864
	ds_read_b128 v[174:177], v146 offset:38912
	s_setprio 1
	s_waitcnt lgkmcnt(3)
	v_mfma_f32_16x16x32_bf16 v[126:129], v[140:143], v[162:165], v[126:129]
	v_mfma_f32_16x16x32_bf16 v[122:125], v[150:153], v[162:165], v[122:125]
	v_mfma_f32_16x16x32_bf16 v[118:121], v[154:157], v[162:165], v[118:121]
	v_mfma_f32_16x16x32_bf16 v[114:117], v[158:161], v[162:165], v[114:117]
	s_waitcnt lgkmcnt(2)
	v_mfma_f32_16x16x32_bf16 v[110:113], v[140:143], v[166:169], v[110:113]
	v_mfma_f32_16x16x32_bf16 v[106:109], v[150:153], v[166:169], v[106:109]
	v_mfma_f32_16x16x32_bf16 v[102:105], v[154:157], v[166:169], v[102:105]
	v_mfma_f32_16x16x32_bf16 v[98:101], v[158:161], v[166:169], v[98:101]
	s_waitcnt lgkmcnt(1)
	v_mfma_f32_16x16x32_bf16 v[94:97], v[140:143], v[170:173], v[94:97]
	v_mfma_f32_16x16x32_bf16 v[90:93], v[150:153], v[170:173], v[90:93]
	v_mfma_f32_16x16x32_bf16 v[86:89], v[154:157], v[170:173], v[86:89]
	v_mfma_f32_16x16x32_bf16 v[82:85], v[158:161], v[170:173], v[82:85]
	s_waitcnt lgkmcnt(0)
	v_mfma_f32_16x16x32_bf16 v[78:81], v[140:143], v[174:177], v[78:81]
	v_mfma_f32_16x16x32_bf16 v[74:77], v[150:153], v[174:177], v[74:77]
	v_mfma_f32_16x16x32_bf16 v[70:73], v[154:157], v[174:177], v[70:73]
	v_mfma_f32_16x16x32_bf16 v[66:69], v[158:161], v[174:177], v[66:69]
	s_setprio 0
	ds_read_b128 v[162:165], v146 offset:40960
	ds_read_b128 v[166:169], v146 offset:43008
	ds_read_b128 v[170:173], v146 offset:45056
	ds_read_b128 v[174:177], v146 offset:47104
	s_setprio 1
	s_waitcnt lgkmcnt(3)
	v_mfma_f32_16x16x32_bf16 v[62:65], v[140:143], v[162:165], v[62:65]
	v_mfma_f32_16x16x32_bf16 v[58:61], v[150:153], v[162:165], v[58:61]
	v_mfma_f32_16x16x32_bf16 v[54:57], v[154:157], v[162:165], v[54:57]
	v_mfma_f32_16x16x32_bf16 v[50:53], v[158:161], v[162:165], v[50:53]
	s_waitcnt lgkmcnt(2)
	v_mfma_f32_16x16x32_bf16 v[46:49], v[140:143], v[166:169], v[46:49]
	v_mfma_f32_16x16x32_bf16 v[42:45], v[150:153], v[166:169], v[42:45]
	v_mfma_f32_16x16x32_bf16 v[38:41], v[154:157], v[166:169], v[38:41]
	v_mfma_f32_16x16x32_bf16 v[34:37], v[158:161], v[166:169], v[34:37]
	s_waitcnt lgkmcnt(1)
	v_mfma_f32_16x16x32_bf16 v[30:33], v[140:143], v[170:173], v[30:33]
	v_mfma_f32_16x16x32_bf16 v[26:29], v[150:153], v[170:173], v[26:29]
	v_mfma_f32_16x16x32_bf16 v[22:25], v[154:157], v[170:173], v[22:25]
	v_mfma_f32_16x16x32_bf16 v[18:21], v[158:161], v[170:173], v[18:21]
	s_waitcnt lgkmcnt(0)
	v_mfma_f32_16x16x32_bf16 v[14:17], v[140:143], v[174:177], v[14:17]
	v_mfma_f32_16x16x32_bf16 v[10:13], v[150:153], v[174:177], v[10:13]
	v_mfma_f32_16x16x32_bf16 v[6:9], v[154:157], v[174:177], v[6:9]
	v_mfma_f32_16x16x32_bf16 v[2:5], v[158:161], v[174:177], v[2:5]
	s_setprio 0
	ds_read_b128 v[140:143], v217 offset:32768
	ds_read_b128 v[150:153], v217 offset:34816
	ds_read_b128 v[154:157], v217 offset:36864
	ds_read_b128 v[158:161], v217 offset:38912
	ds_read_b128 v[162:165], v216 offset:32768
	ds_read_b128 v[166:169], v216 offset:34816
	ds_read_b128 v[170:173], v216 offset:36864
	ds_read_b128 v[174:177], v216 offset:38912
	s_setprio 1
	s_waitcnt lgkmcnt(3)
	v_mfma_f32_16x16x32_bf16 v[126:129], v[140:143], v[162:165], v[126:129]
	v_mfma_f32_16x16x32_bf16 v[122:125], v[150:153], v[162:165], v[122:125]
	v_mfma_f32_16x16x32_bf16 v[118:121], v[154:157], v[162:165], v[118:121]
	v_mfma_f32_16x16x32_bf16 v[114:117], v[158:161], v[162:165], v[114:117]
	s_waitcnt lgkmcnt(2)
	v_mfma_f32_16x16x32_bf16 v[110:113], v[140:143], v[166:169], v[110:113]
	v_mfma_f32_16x16x32_bf16 v[106:109], v[150:153], v[166:169], v[106:109]
	v_mfma_f32_16x16x32_bf16 v[102:105], v[154:157], v[166:169], v[102:105]
	v_mfma_f32_16x16x32_bf16 v[98:101], v[158:161], v[166:169], v[98:101]
	s_waitcnt lgkmcnt(1)
	v_mfma_f32_16x16x32_bf16 v[94:97], v[140:143], v[170:173], v[94:97]
	v_mfma_f32_16x16x32_bf16 v[162:165], v[150:153], v[170:173], v[90:93]
	v_mfma_f32_16x16x32_bf16 v[86:89], v[154:157], v[170:173], v[86:89]
	v_mfma_f32_16x16x32_bf16 v[82:85], v[158:161], v[170:173], v[82:85]
	s_waitcnt lgkmcnt(0)
	v_mfma_f32_16x16x32_bf16 v[78:81], v[140:143], v[174:177], v[78:81]
	v_mfma_f32_16x16x32_bf16 v[74:77], v[150:153], v[174:177], v[74:77]
	v_mfma_f32_16x16x32_bf16 v[70:73], v[154:157], v[174:177], v[70:73]
	v_mfma_f32_16x16x32_bf16 v[66:69], v[158:161], v[174:177], v[66:69]
	s_setprio 0
	ds_read_b128 v[90:93], v216 offset:40960
	ds_read_b128 v[166:169], v216 offset:43008
	ds_read_b128 v[170:173], v216 offset:45056
	ds_read_b128 v[174:177], v216 offset:47104
	s_setprio 1
	s_waitcnt lgkmcnt(3)
	v_mfma_f32_16x16x32_bf16 v[62:65], v[140:143], v[90:93], v[62:65]
	v_mfma_f32_16x16x32_bf16 v[58:61], v[150:153], v[90:93], v[58:61]
	v_mfma_f32_16x16x32_bf16 v[54:57], v[154:157], v[90:93], v[54:57]
	v_mfma_f32_16x16x32_bf16 v[50:53], v[158:161], v[90:93], v[50:53]
	s_waitcnt lgkmcnt(2)
	v_mfma_f32_16x16x32_bf16 v[46:49], v[140:143], v[166:169], v[46:49]
	v_mfma_f32_16x16x32_bf16 v[42:45], v[150:153], v[166:169], v[42:45]
	v_mfma_f32_16x16x32_bf16 v[38:41], v[154:157], v[166:169], v[38:41]
	v_mfma_f32_16x16x32_bf16 v[34:37], v[158:161], v[166:169], v[34:37]
	s_waitcnt lgkmcnt(1)
	v_mfma_f32_16x16x32_bf16 v[30:33], v[140:143], v[170:173], v[30:33]
	v_mfma_f32_16x16x32_bf16 v[26:29], v[150:153], v[170:173], v[26:29]
	v_mfma_f32_16x16x32_bf16 v[22:25], v[154:157], v[170:173], v[22:25]
	v_mfma_f32_16x16x32_bf16 v[18:21], v[158:161], v[170:173], v[18:21]
	s_waitcnt lgkmcnt(0)
	v_mfma_f32_16x16x32_bf16 v[14:17], v[140:143], v[174:177], v[14:17]
	v_mfma_f32_16x16x32_bf16 v[10:13], v[150:153], v[174:177], v[10:13]
	v_mfma_f32_16x16x32_bf16 v[6:9], v[154:157], v[174:177], v[6:9]
	v_mfma_f32_16x16x32_bf16 v[2:5], v[158:161], v[174:177], v[2:5]
	s_setprio 0
	v_mul_f32_e32 v93, 0xbfb8aa3b, v126
	v_exp_f32_e32 v93, v93
	v_mul_f32_e32 v130, 0xbfb8aa3b, v127
	v_exp_f32_e32 v130, v130
	v_mul_f32_e32 v141, 0xbfb8aa3b, v129
	v_add_f32_e32 v93, 1.0, v93
	v_rcp_f32_e32 v140, v93
	v_add_f32_e32 v93, 1.0, v130
	v_mul_f32_e32 v130, 0xbfb8aa3b, v128
	v_exp_f32_e32 v130, v130
	v_exp_f32_e32 v143, v141
	v_rcp_f32_e32 v141, v93
	v_or_b32_e32 v90, s38, v148
	v_add_f32_e32 v93, 1.0, v130
	v_rcp_f32_e32 v142, v93
	v_add_f32_e32 v93, 1.0, v143
	v_rcp_f32_e32 v143, v93
	v_pk_mul_f32 v[126:127], v[126:127], v[140:141]
	v_mul_f32_e32 v93, 0xbfb8aa3b, v118
	v_pk_mul_f32 v[122:123], v[122:123], v[126:127]
	v_pk_mul_f32 v[126:127], v[128:129], v[142:143]
	v_cvt_pk_bf16_f32 v122, v122, v123
	v_exp_f32_e32 v93, v93
	v_mul_f32_e32 v123, 0xbfb8aa3b, v119
	v_pk_mul_f32 v[124:125], v[124:125], v[126:127]
	v_exp_f32_e32 v126, v123
	v_cvt_pk_bf16_f32 v123, v124, v125
	v_add_f32_e32 v93, 1.0, v93
	v_mul_f32_e32 v125, 0xbfb8aa3b, v120
	v_rcp_f32_e32 v124, v93
	v_add_f32_e32 v93, 1.0, v126
	v_exp_f32_e32 v126, v125
	v_mul_f32_e32 v125, 0xbfb8aa3b, v121
	v_exp_f32_e32 v127, v125
	v_rcp_f32_e32 v125, v93
	v_add_f32_e32 v93, 1.0, v126
	v_rcp_f32_e32 v126, v93
	v_add_f32_e32 v93, 1.0, v127
	v_rcp_f32_e32 v127, v93
	v_ashrrev_i32_e32 v90, 1, v90
	v_pk_mul_f32 v[118:119], v[118:119], v[124:125]
	v_ashrrev_i32_e32 v91, 31, v90
	v_pk_mul_f32 v[114:115], v[114:115], v[118:119]
	v_pk_mul_f32 v[118:119], v[120:121], v[126:127]
	v_add_u32_e32 v92, s37, v149
	v_lshl_add_u64 v[90:91], v[90:91], 1, v[136:137]
	v_pk_mul_f32 v[116:117], v[116:117], v[118:119]
	v_mad_i64_i32 v[150:151], s[0:1], v92, s36, v[90:91]
	v_cvt_pk_bf16_f32 v114, v114, v115
	v_cvt_pk_bf16_f32 v115, v116, v117
	v_mul_f32_e32 v93, 0xbfb8aa3b, v110
	s_barrier
	global_store_dwordx2 v[150:151], v[114:115], off offset:32
	v_exp_f32_e32 v93, v93
	v_mul_f32_e32 v114, 0xbfb8aa3b, v111
	v_exp_f32_e32 v115, v114
	v_or_b32_e32 v118, 16, v92
	v_add_f32_e32 v93, 1.0, v93
	v_rcp_f32_e32 v114, v93
	v_add_f32_e32 v93, 1.0, v115
	v_mul_f32_e32 v115, 0xbfb8aa3b, v112
	v_exp_f32_e32 v116, v115
	v_mul_f32_e32 v115, 0xbfb8aa3b, v113
	v_exp_f32_e32 v117, v115
	v_rcp_f32_e32 v115, v93
	v_add_f32_e32 v93, 1.0, v116
	v_rcp_f32_e32 v116, v93
	v_add_f32_e32 v93, 1.0, v117
	v_rcp_f32_e32 v117, v93
	v_pk_mul_f32 v[110:111], v[110:111], v[114:115]
	v_mul_f32_e32 v93, 0xbfb8aa3b, v102
	v_pk_mul_f32 v[106:107], v[106:107], v[110:111]
	v_pk_mul_f32 v[110:111], v[112:113], v[116:117]
	v_cvt_pk_bf16_f32 v106, v106, v107
	v_exp_f32_e32 v93, v93
	v_mul_f32_e32 v107, 0xbfb8aa3b, v103
	v_pk_mul_f32 v[108:109], v[108:109], v[110:111]
	v_exp_f32_e32 v110, v107
	v_cvt_pk_bf16_f32 v107, v108, v109
	v_add_f32_e32 v93, 1.0, v93
	v_mul_f32_e32 v109, 0xbfb8aa3b, v104
	v_rcp_f32_e32 v108, v93
	v_add_f32_e32 v93, 1.0, v110
	v_exp_f32_e32 v110, v109
	v_mul_f32_e32 v109, 0xbfb8aa3b, v105
	v_exp_f32_e32 v111, v109
	v_rcp_f32_e32 v109, v93
	v_add_f32_e32 v93, 1.0, v110
	v_rcp_f32_e32 v110, v93
	v_add_f32_e32 v93, 1.0, v111
	v_rcp_f32_e32 v111, v93
	v_pk_mul_f32 v[102:103], v[102:103], v[108:109]
	v_mad_i64_i32 v[118:119], s[0:1], v118, s36, v[90:91]
	v_pk_mul_f32 v[98:99], v[98:99], v[102:103]
	v_pk_mul_f32 v[102:103], v[104:105], v[110:111]
	v_cvt_pk_bf16_f32 v98, v98, v99
	v_pk_mul_f32 v[100:101], v[100:101], v[102:103]
	v_mul_f32_e32 v93, 0xbfb8aa3b, v94
	v_cvt_pk_bf16_f32 v99, v100, v101
	global_store_dwordx2 v[118:119], v[98:99], off offset:32
	v_exp_f32_e32 v93, v93
	v_mul_f32_e32 v98, 0xbfb8aa3b, v95
	v_exp_f32_e32 v99, v98
	v_or_b32_e32 v102, 32, v92
	v_add_f32_e32 v93, 1.0, v93
	v_rcp_f32_e32 v98, v93
	v_add_f32_e32 v93, 1.0, v99
	v_mul_f32_e32 v99, 0xbfb8aa3b, v96
	v_exp_f32_e32 v100, v99
	v_mul_f32_e32 v99, 0xbfb8aa3b, v97
	v_exp_f32_e32 v101, v99
	v_rcp_f32_e32 v99, v93
	v_add_f32_e32 v93, 1.0, v100
	v_rcp_f32_e32 v100, v93
	v_add_f32_e32 v93, 1.0, v101
	v_rcp_f32_e32 v101, v93
	v_pk_mul_f32 v[94:95], v[94:95], v[98:99]
	v_mul_f32_e32 v93, 0xbfb8aa3b, v86
	v_pk_mul_f32 v[94:95], v[162:163], v[94:95]
	v_exp_f32_e32 v93, v93
	v_cvt_pk_bf16_f32 v94, v94, v95
	v_mul_f32_e32 v95, 0xbfb8aa3b, v87
	v_exp_f32_e32 v98, v95
	v_pk_mul_f32 v[96:97], v[96:97], v[100:101]
	v_add_f32_e32 v93, 1.0, v93
	v_pk_mul_f32 v[96:97], v[164:165], v[96:97]
	v_mad_i64_i32 v[102:103], s[0:1], v102, s36, v[90:91]
	v_cvt_pk_bf16_f32 v95, v96, v97
	v_mul_f32_e32 v97, 0xbfb8aa3b, v88
	v_rcp_f32_e32 v96, v93
	v_add_f32_e32 v93, 1.0, v98
	v_exp_f32_e32 v98, v97
	v_mul_f32_e32 v97, 0xbfb8aa3b, v89
	v_exp_f32_e32 v99, v97
	v_rcp_f32_e32 v97, v93
	v_add_f32_e32 v93, 1.0, v98
	v_rcp_f32_e32 v98, v93
	v_add_f32_e32 v93, 1.0, v99
	v_rcp_f32_e32 v99, v93
	v_pk_mul_f32 v[86:87], v[86:87], v[96:97]
	s_add_i32 s3, s3, s7
	v_pk_mul_f32 v[82:83], v[82:83], v[86:87]
	v_pk_mul_f32 v[86:87], v[88:89], v[98:99]
	v_cvt_pk_bf16_f32 v82, v82, v83
	v_pk_mul_f32 v[84:85], v[84:85], v[86:87]
	v_or_b32_e32 v86, 48, v92
	v_cvt_pk_bf16_f32 v83, v84, v85
	global_store_dwordx2 v[102:103], v[82:83], off offset:32
	v_mul_f32_e32 v82, 0xbfb8aa3b, v78
	v_mul_f32_e32 v83, 0xbfb8aa3b, v79
	v_exp_f32_e32 v82, v82
	v_exp_f32_e32 v83, v83
	v_mul_f32_e32 v84, 0xbfb8aa3b, v80
	v_mul_f32_e32 v85, 0xbfb8aa3b, v81
	v_exp_f32_e32 v84, v84
	v_exp_f32_e32 v85, v85
	v_add_f32_e32 v82, 1.0, v82
	v_add_f32_e32 v83, 1.0, v83
	v_rcp_f32_e32 v82, v82
	v_rcp_f32_e32 v83, v83
	v_add_f32_e32 v84, 1.0, v84
	v_add_f32_e32 v85, 1.0, v85
	v_rcp_f32_e32 v84, v84
	v_rcp_f32_e32 v85, v85
	v_pk_mul_f32 v[78:79], v[78:79], v[82:83]
	v_mad_i64_i32 v[86:87], s[0:1], v86, s36, v[90:91]
	v_pk_mul_f32 v[74:75], v[74:75], v[78:79]
	v_pk_mul_f32 v[78:79], v[80:81], v[84:85]
	v_cvt_pk_bf16_f32 v74, v74, v75
	v_mul_f32_e32 v75, 0xbfb8aa3b, v70
	v_pk_mul_f32 v[76:77], v[76:77], v[78:79]
	v_exp_f32_e32 v78, v75
	v_mul_f32_e32 v75, 0xbfb8aa3b, v71
	v_exp_f32_e32 v79, v75
	v_cvt_pk_bf16_f32 v75, v76, v77
	v_add_f32_e32 v76, 1.0, v78
	v_mul_f32_e32 v78, 0xbfb8aa3b, v72
	v_add_f32_e32 v77, 1.0, v79
	v_mul_f32_e32 v79, 0xbfb8aa3b, v73
	v_exp_f32_e32 v78, v78
	v_exp_f32_e32 v79, v79
	v_rcp_f32_e32 v76, v76
	v_rcp_f32_e32 v77, v77
	v_add_f32_e32 v78, 1.0, v78
	v_add_f32_e32 v79, 1.0, v79
	v_rcp_f32_e32 v78, v78
	v_rcp_f32_e32 v79, v79
	v_pk_mul_f32 v[70:71], v[70:71], v[76:77]
	s_add_i32 s8, s8, s7
	v_pk_mul_f32 v[66:67], v[66:67], v[70:71]
	v_pk_mul_f32 v[70:71], v[72:73], v[78:79]
	v_cvt_pk_bf16_f32 v66, v66, v67
	v_pk_mul_f32 v[68:69], v[68:69], v[70:71]
	v_or_b32_e32 v70, 64, v92
	v_cvt_pk_bf16_f32 v67, v68, v69
	global_store_dwordx2 v[86:87], v[66:67], off offset:32
	v_mul_f32_e32 v66, 0xbfb8aa3b, v62
	v_mul_f32_e32 v67, 0xbfb8aa3b, v63
	v_exp_f32_e32 v66, v66
	v_exp_f32_e32 v67, v67
	v_mul_f32_e32 v68, 0xbfb8aa3b, v64
	v_mul_f32_e32 v69, 0xbfb8aa3b, v65
	v_exp_f32_e32 v68, v68
	v_exp_f32_e32 v69, v69
	v_add_f32_e32 v66, 1.0, v66
	v_add_f32_e32 v67, 1.0, v67
	v_rcp_f32_e32 v66, v66
	v_rcp_f32_e32 v67, v67
	v_add_f32_e32 v68, 1.0, v68
	v_add_f32_e32 v69, 1.0, v69
	v_rcp_f32_e32 v68, v68
	v_rcp_f32_e32 v69, v69
	v_pk_mul_f32 v[62:63], v[62:63], v[66:67]
	v_mad_i64_i32 v[70:71], s[0:1], v70, s36, v[90:91]
	v_pk_mul_f32 v[58:59], v[58:59], v[62:63]
	v_pk_mul_f32 v[62:63], v[64:65], v[68:69]
	v_cvt_pk_bf16_f32 v58, v58, v59
	v_mul_f32_e32 v59, 0xbfb8aa3b, v54
	v_pk_mul_f32 v[60:61], v[60:61], v[62:63]
	v_exp_f32_e32 v62, v59
	v_mul_f32_e32 v59, 0xbfb8aa3b, v55
	v_exp_f32_e32 v63, v59
	v_cvt_pk_bf16_f32 v59, v60, v61
	v_add_f32_e32 v60, 1.0, v62
	v_mul_f32_e32 v62, 0xbfb8aa3b, v56
	v_add_f32_e32 v61, 1.0, v63
	v_mul_f32_e32 v63, 0xbfb8aa3b, v57
	v_exp_f32_e32 v62, v62
	v_exp_f32_e32 v63, v63
	v_rcp_f32_e32 v60, v60
	v_rcp_f32_e32 v61, v61
	v_add_f32_e32 v62, 1.0, v62
	v_add_f32_e32 v63, 1.0, v63
	v_rcp_f32_e32 v62, v62
	v_rcp_f32_e32 v63, v63
	v_pk_mul_f32 v[54:55], v[54:55], v[60:61]
	s_cmpk_gt_i32 s3, 0x2d5
	v_pk_mul_f32 v[50:51], v[50:51], v[54:55]
	v_pk_mul_f32 v[54:55], v[56:57], v[62:63]
	v_cvt_pk_bf16_f32 v50, v50, v51
	v_pk_mul_f32 v[52:53], v[52:53], v[54:55]
	v_or_b32_e32 v54, 0x50, v92
	v_cvt_pk_bf16_f32 v51, v52, v53
	global_store_dwordx2 v[70:71], v[50:51], off offset:32
	v_mul_f32_e32 v50, 0xbfb8aa3b, v46
	v_mul_f32_e32 v51, 0xbfb8aa3b, v47
	v_exp_f32_e32 v50, v50
	v_exp_f32_e32 v51, v51
	v_mul_f32_e32 v52, 0xbfb8aa3b, v48
	v_mul_f32_e32 v53, 0xbfb8aa3b, v49
	v_exp_f32_e32 v52, v52
	v_exp_f32_e32 v53, v53
	v_add_f32_e32 v50, 1.0, v50
	v_add_f32_e32 v51, 1.0, v51
	v_rcp_f32_e32 v50, v50
	v_rcp_f32_e32 v51, v51
	v_add_f32_e32 v52, 1.0, v52
	v_add_f32_e32 v53, 1.0, v53
	v_rcp_f32_e32 v52, v52
	v_rcp_f32_e32 v53, v53
	v_pk_mul_f32 v[46:47], v[46:47], v[50:51]
	v_mad_i64_i32 v[54:55], s[0:1], v54, s36, v[90:91]
	v_pk_mul_f32 v[42:43], v[42:43], v[46:47]
	v_pk_mul_f32 v[46:47], v[48:49], v[52:53]
	v_cvt_pk_bf16_f32 v42, v42, v43
	v_mul_f32_e32 v43, 0xbfb8aa3b, v38
	v_pk_mul_f32 v[44:45], v[44:45], v[46:47]
	v_exp_f32_e32 v46, v43
	v_mul_f32_e32 v43, 0xbfb8aa3b, v39
	v_exp_f32_e32 v47, v43
	v_cvt_pk_bf16_f32 v43, v44, v45
	v_add_f32_e32 v44, 1.0, v46
	v_mul_f32_e32 v46, 0xbfb8aa3b, v40
	v_add_f32_e32 v45, 1.0, v47
	v_mul_f32_e32 v47, 0xbfb8aa3b, v41
	v_exp_f32_e32 v46, v46
	v_exp_f32_e32 v47, v47
	v_rcp_f32_e32 v44, v44
	v_rcp_f32_e32 v45, v45
	v_add_f32_e32 v46, 1.0, v46
	v_add_f32_e32 v47, 1.0, v47
	v_rcp_f32_e32 v46, v46
	v_rcp_f32_e32 v47, v47
	v_pk_mul_f32 v[38:39], v[38:39], v[44:45]
	global_store_dwordx2 v[150:151], v[122:123], off
	v_pk_mul_f32 v[34:35], v[34:35], v[38:39]
	v_pk_mul_f32 v[38:39], v[40:41], v[46:47]
	v_cvt_pk_bf16_f32 v34, v34, v35
	v_pk_mul_f32 v[36:37], v[36:37], v[38:39]
	v_or_b32_e32 v38, 0x60, v92
	v_cvt_pk_bf16_f32 v35, v36, v37
	global_store_dwordx2 v[54:55], v[34:35], off offset:32
	v_mul_f32_e32 v34, 0xbfb8aa3b, v30
	v_mul_f32_e32 v35, 0xbfb8aa3b, v31
	v_exp_f32_e32 v34, v34
	v_exp_f32_e32 v35, v35
	v_mul_f32_e32 v36, 0xbfb8aa3b, v32
	v_mul_f32_e32 v37, 0xbfb8aa3b, v33
	v_exp_f32_e32 v36, v36
	v_exp_f32_e32 v37, v37
	v_add_f32_e32 v34, 1.0, v34
	v_add_f32_e32 v35, 1.0, v35
	v_rcp_f32_e32 v34, v34
	v_rcp_f32_e32 v35, v35
	v_add_f32_e32 v36, 1.0, v36
	v_add_f32_e32 v37, 1.0, v37
	v_rcp_f32_e32 v36, v36
	v_rcp_f32_e32 v37, v37
	v_pk_mul_f32 v[30:31], v[30:31], v[34:35]
	v_mad_i64_i32 v[38:39], s[0:1], v38, s36, v[90:91]
	v_pk_mul_f32 v[26:27], v[26:27], v[30:31]
	v_pk_mul_f32 v[30:31], v[32:33], v[36:37]
	v_cvt_pk_bf16_f32 v26, v26, v27
	v_mul_f32_e32 v27, 0xbfb8aa3b, v22
	v_pk_mul_f32 v[28:29], v[28:29], v[30:31]
	v_exp_f32_e32 v30, v27
	v_mul_f32_e32 v27, 0xbfb8aa3b, v23
	v_exp_f32_e32 v31, v27
	v_cvt_pk_bf16_f32 v27, v28, v29
	v_add_f32_e32 v28, 1.0, v30
	v_mul_f32_e32 v30, 0xbfb8aa3b, v24
	v_add_f32_e32 v29, 1.0, v31
	v_mul_f32_e32 v31, 0xbfb8aa3b, v25
	v_exp_f32_e32 v30, v30
	v_exp_f32_e32 v31, v31
	v_rcp_f32_e32 v28, v28
	v_rcp_f32_e32 v29, v29
	v_add_f32_e32 v30, 1.0, v30
	v_add_f32_e32 v31, 1.0, v31
	v_rcp_f32_e32 v30, v30
	v_rcp_f32_e32 v31, v31
	v_pk_mul_f32 v[22:23], v[22:23], v[28:29]
	global_store_dwordx2 v[118:119], v[106:107], off
	v_pk_mul_f32 v[18:19], v[18:19], v[22:23]
	v_pk_mul_f32 v[22:23], v[24:25], v[30:31]
	v_cvt_pk_bf16_f32 v18, v18, v19
	v_pk_mul_f32 v[20:21], v[20:21], v[22:23]
	v_or_b32_e32 v22, 0x70, v92
	v_cvt_pk_bf16_f32 v19, v20, v21
	global_store_dwordx2 v[38:39], v[18:19], off offset:32
	v_mul_f32_e32 v18, 0xbfb8aa3b, v14
	v_mul_f32_e32 v19, 0xbfb8aa3b, v15
	v_exp_f32_e32 v18, v18
	v_exp_f32_e32 v19, v19
	v_mul_f32_e32 v20, 0xbfb8aa3b, v16
	v_mul_f32_e32 v21, 0xbfb8aa3b, v17
	v_exp_f32_e32 v20, v20
	v_exp_f32_e32 v21, v21
	v_add_f32_e32 v18, 1.0, v18
	v_add_f32_e32 v19, 1.0, v19
	v_rcp_f32_e32 v18, v18
	v_rcp_f32_e32 v19, v19
	v_add_f32_e32 v20, 1.0, v20
	v_add_f32_e32 v21, 1.0, v21
	v_rcp_f32_e32 v20, v20
	v_rcp_f32_e32 v21, v21
	v_pk_mul_f32 v[14:15], v[14:15], v[18:19]
	v_mad_i64_i32 v[22:23], s[0:1], v22, s36, v[90:91]
	v_pk_mul_f32 v[10:11], v[10:11], v[14:15]
	v_pk_mul_f32 v[14:15], v[16:17], v[20:21]
	v_cvt_pk_bf16_f32 v10, v10, v11
	v_mul_f32_e32 v11, 0xbfb8aa3b, v6
	v_pk_mul_f32 v[12:13], v[12:13], v[14:15]
	v_exp_f32_e32 v14, v11
	v_mul_f32_e32 v11, 0xbfb8aa3b, v7
	v_exp_f32_e32 v15, v11
	v_cvt_pk_bf16_f32 v11, v12, v13
	v_add_f32_e32 v12, 1.0, v14
	v_mul_f32_e32 v14, 0xbfb8aa3b, v8
	v_add_f32_e32 v13, 1.0, v15
	v_mul_f32_e32 v15, 0xbfb8aa3b, v9
	v_exp_f32_e32 v14, v14
	v_exp_f32_e32 v15, v15
	v_rcp_f32_e32 v12, v12
	v_rcp_f32_e32 v13, v13
	v_add_f32_e32 v14, 1.0, v14
	v_add_f32_e32 v15, 1.0, v15
	v_rcp_f32_e32 v14, v14
	v_rcp_f32_e32 v15, v15
	v_pk_mul_f32 v[6:7], v[6:7], v[12:13]
	global_store_dwordx2 v[102:103], v[94:95], off
	v_pk_mul_f32 v[2:3], v[2:3], v[6:7]
	v_pk_mul_f32 v[6:7], v[8:9], v[14:15]
	v_cvt_pk_bf16_f32 v2, v2, v3
	v_pk_mul_f32 v[4:5], v[4:5], v[6:7]
	global_store_dwordx2 v[86:87], v[74:75], off
	v_cvt_pk_bf16_f32 v3, v4, v5
	global_store_dwordx2 v[70:71], v[58:59], off
	global_store_dwordx2 v[54:55], v[42:43], off
	global_store_dwordx2 v[38:39], v[26:27], off
	global_store_dwordx2 v[22:23], v[10:11], off
	global_store_dwordx2 v[22:23], v[2:3], off offset:32
	s_cbranch_scc0 .LBB0_354

.LBB0_747:
	v_mov_b32_e32 v3, v2
	s_cmpk_gt_u32 s2, 0x15ff
	s_cbranch_scc1 .LBB0_752
	v_lshlrev_b32_e32 v4, 4, v2
	v_and_b32_e32 v130, 0x70, v4
	v_mov_b32_e32 v131, 0
	v_lshl_add_u64 v[4:5], s[86:87], 0, v[130:131]
	s_mov_b64 s[0:1], 0x4450000
	v_lshrrev_b32_e32 v1, 3, v2
	v_lshl_add_u64 v[132:133], v[4:5], 0, s[0:1]
	s_mov_b64 s[0:1], 0x1000000
	v_lshl_add_u64 v[134:135], v[4:5], 0, s[0:1]
	v_mul_u32_u24_e32 v4, 0x48, v1
	v_lshlrev_b32_e32 v4, 1, v4
	s_add_i32 s0, 0, 0x12000
	v_add3_u32 v144, 0, v4, v130
	v_add3_u32 v145, s0, v4, v130
	v_and_b32_e32 v4, 15, v2
	v_lshrrev_b32_e32 v5, 1, v2
	s_movk_i32 s1, 0x180
	v_and_or_b32 v4, v5, s1, v4
	v_mul_u32_u24_e32 v4, 0x90, v4
	v_and_b32_e32 v5, 48, v2
	v_add3_u32 v146, 0, v4, v5
	v_and_b32_e32 v4, 0xcf, v2
	v_mul_u32_u24_e32 v4, 0x90, v4
	v_add3_u32 v147, s0, v4, v5
	v_lshrrev_b32_e32 v4, 1, v1
	v_and_b32_e32 v4, 7, v4
	v_and_b32_e32 v5, 7, v2
	v_xor_b32_e32 v4, v4, v5
	v_lshlrev_b32_e32 v4, 4, v4
	v_lshl_add_u32 v144, v1, 7, v4
	v_add_u32_e32 v145, 0x10000, v144
	v_and_b32_e32 v4, 15, v2
	v_lshrrev_b32_e32 v5, 1, v4
	v_bfe_u32 v216, v2, 4, 2
	v_xor_b32_e32 v5, v5, v216
	v_lshlrev_b32_e32 v5, 4, v5
	v_lshrrev_b32_e32 v216, 8, v2
	v_lshl_add_u32 v216, v216, 7, v4
	v_lshl_add_u32 v146, v216, 7, v5
	v_xor_b32_e32 v216, 64, v146
	v_bfe_u32 v217, v2, 6, 2
	v_lshl_add_u32 v217, v217, 6, v4
	v_lshl_add_u32 v147, v217, 7, v5
	v_add_u32_e32 v147, 0x10000, v147
	v_xor_b32_e32 v217, 64, v147
	v_ashrrev_i32_e32 v4, 1, v3
	v_and_b32_e32 v148, 0xc0, v3
	v_and_b32_e32 v5, 15, v3
	v_lshrrev_b32_e32 v3, 1, v3
	s_movk_i32 s0, 0xff80
	v_and_b32_e32 v130, 24, v3
	s_lshr_b32 s3, s2, 3
	s_and_b32 s8, s2, 7
	v_and_or_b32 v149, v4, s0, v5
	v_lshl_add_u64 v[4:5], s[86:87], 0, v[130:131]
	s_mov_b64 s[0:1], 0x1d050000
	s_mul_i32 s6, s8, 33
	v_lshl_add_u64 v[136:137], v[4:5], 0, s[0:1]
	s_mulk_i32 s8, 0x2100
	s_lshl_b32 s0, s3, 8
	v_and_b32_e32 v2, 7, v2
	s_add_i32 s0, s0, s8
	s_ashr_i32 s7, s33, 3
	v_lshlrev_b32_e32 v130, 4, v2
	v_add_u32_e32 v2, s0, v1
	s_add_i32 s6, s6, 1
	v_lshl_add_u64 v[138:139], s[86:87], 0, v[130:131]
	v_add_u32_e32 v130, 0x100, v2
	s_lshl_b32 s8, s7, 8
	s_mov_b32 s9, 0x20000
	s_mov_b32 s10, 0x40000
	s_mov_b32 s11, 0x60000
	s_mov_b32 s12, 0x4450000
	s_mov_b32 s13, 0x4470000
	s_mov_b32 s14, 0x4490000
	s_mov_b32 s15, 0x44b0000
	s_waitcnt lgkmcnt(0)
	s_mov_b32 s16, 0x1000000
	s_mov_b32 s17, 0x1020000
	s_mov_b32 s18, 0x1040000
	s_mov_b32 s19, 0x1060000
	s_movk_i32 s20, 0x1600
.LBB0_749:
	s_mul_hi_i32 s0, s3, 0x2e8ba2e9
	s_lshr_b32 s1, s0, 31
	s_ashr_i32 s0, s0, 4
	s_add_i32 s24, s0, s1
	s_mul_i32 s1, s24, 0xffffffa8
	s_add_i32 s1, s1, s3
	s_ashr_i32 s21, s1, 31
	s_lshl_b32 s0, s24, 2
	s_lshr_b32 s21, s21, 30
	s_add_i32 s21, s1, s21
	s_add_i32 s0, s6, s0
	s_ashr_i32 s22, s21, 2
	s_add_i32 s0, s0, s1
	s_lshl_b32 s25, s22, 10
	s_lshl_b32 s0, s0, 8
	s_sub_i32 s21, s0, s25
	v_or_b32_e32 v2, s21, v1
	v_ashrrev_i32_e32 v3, 31, v2
	v_lshlrev_b64 v[2:3], 11, v[2:3]
	v_lshl_add_u64 v[2:3], v[132:133], 0, v[2:3]
	v_add_co_u32_e32 v6, vcc, s9, v2
	s_lshl_b32 s22, s22, 8
	s_nop 0
	v_addc_co_u32_e32 v7, vcc, 0, v3, vcc
	v_or_b32_e32 v4, s22, v1
	global_load_dwordx4 v[20:23], v[2:3], off
	global_load_dwordx4 v[24:27], v[6:7], off
	v_add_co_u32_e32 v6, vcc, s10, v2
	v_ashrrev_i32_e32 v5, 31, v4
	s_nop 0
	v_addc_co_u32_e32 v7, vcc, 0, v3, vcc
	v_lshlrev_b64 v[52:53], 11, v[4:5]
	v_add_co_u32_e32 v2, vcc, s11, v2
	v_lshl_add_u64 v[4:5], v[134:135], 0, v[52:53]
	s_nop 0
	v_addc_co_u32_e32 v3, vcc, 0, v3, vcc
	global_load_dwordx4 v[28:31], v[6:7], off
	global_load_dwordx4 v[32:35], v[2:3], off
	v_add_co_u32_e32 v2, vcc, s9, v4
	s_waitcnt vmcnt(63) expcnt(7) lgkmcnt(15)
	s_nop 0
	v_addc_co_u32_e32 v3, vcc, 0, v5, vcc
	s_barrier
	global_load_dwordx4 v[36:39], v[4:5], off
	global_load_dwordx4 v[40:43], v[2:3], off
	v_add_co_u32_e32 v2, vcc, s10, v4
	s_mulk_i32 s24, 0x5400
	s_nop 0
	v_addc_co_u32_e32 v3, vcc, 0, v5, vcc
	v_add_co_u32_e32 v4, vcc, s11, v4
	v_subrev_u32_e32 v19, s25, v130
	s_nop 0
	v_addc_co_u32_e32 v5, vcc, 0, v5, vcc
	global_load_dwordx4 v[44:47], v[2:3], off
	global_load_dwordx4 v[48:51], v[4:5], off
	v_subrev_u32_e32 v54, s24, v19
	v_ashrrev_i32_e32 v55, 31, v54
	v_lshlrev_b64 v[54:55], 11, v[54:55]
	s_mov_b64 s[0:1], 0
	s_mov_b32 s23, 0
	v_mov_b32_e32 v2, 0
	v_mov_b32_e32 v3, v131
	v_mov_b32_e32 v4, v131
	v_mov_b32_e32 v5, v131
	v_mov_b32_e32 v6, 0
	v_mov_b32_e32 v7, v131
	v_mov_b32_e32 v8, v131
	v_mov_b32_e32 v9, v131
	v_mov_b32_e32 v10, 0
	v_mov_b32_e32 v11, v131
	v_mov_b32_e32 v12, v131
	v_mov_b32_e32 v13, v131
	v_mov_b32_e32 v14, 0
	v_mov_b32_e32 v15, v131
	v_mov_b32_e32 v16, v131
	v_mov_b32_e32 v17, v131
	v_mov_b32_e32 v18, 0
	v_lshl_add_u64 v[140:141], v[138:139], 0, v[52:53]
	v_lshl_add_u64 v[142:143], v[138:139], 0, v[54:55]
	v_mov_b32_e32 v19, v131
	v_mov_b32_e32 v52, v131
	v_mov_b32_e32 v53, v131
	v_mov_b32_e32 v54, 0
	v_mov_b32_e32 v55, v131
	v_mov_b32_e32 v56, v131
	v_mov_b32_e32 v57, v131
	v_mov_b32_e32 v58, 0
	v_mov_b32_e32 v59, v131
	v_mov_b32_e32 v60, v131
	v_mov_b32_e32 v61, v131
	v_mov_b32_e32 v62, 0
	v_mov_b32_e32 v63, v131
	v_mov_b32_e32 v64, v131
	v_mov_b32_e32 v65, v131
	v_mov_b32_e32 v66, 0
	v_mov_b32_e32 v67, v131
	v_mov_b32_e32 v68, v131
	v_mov_b32_e32 v69, v131
	v_mov_b32_e32 v70, 0
	v_mov_b32_e32 v71, v131
	v_mov_b32_e32 v72, v131
	v_mov_b32_e32 v73, v131
	v_mov_b32_e32 v74, 0
	s_waitcnt vmcnt(7)
	ds_write_b128 v144, v[20:23]
	s_waitcnt vmcnt(6)
	ds_write_b128 v144, v[24:27] offset:8192
	s_waitcnt vmcnt(5)
	ds_write_b128 v144, v[28:31] offset:16384
	s_waitcnt vmcnt(4)
	ds_write_b128 v144, v[32:35] offset:24576
	s_waitcnt vmcnt(3)
	ds_write_b128 v145, v[36:39]
	s_waitcnt vmcnt(2)
	ds_write_b128 v145, v[40:43] offset:8192
	s_waitcnt vmcnt(1)
	ds_write_b128 v145, v[44:47] offset:16384
	s_waitcnt vmcnt(0)
	ds_write_b128 v145, v[48:51] offset:24576
	v_mov_b32_e32 v20, v131
	v_mov_b32_e32 v21, v131
	v_mov_b32_e32 v22, 0
	v_mov_b32_e32 v23, v131
	v_mov_b32_e32 v24, v131
	v_mov_b32_e32 v25, v131
	v_mov_b32_e32 v26, 0
	v_mov_b32_e32 v27, v131
	v_mov_b32_e32 v28, v131
	v_mov_b32_e32 v29, v131
	v_mov_b32_e32 v30, 0
	v_mov_b32_e32 v31, v131
	v_mov_b32_e32 v32, v131
	v_mov_b32_e32 v33, v131
	v_mov_b32_e32 v34, 0
	v_mov_b32_e32 v35, v131
	v_mov_b32_e32 v36, v131
	v_mov_b32_e32 v37, v131
	v_mov_b32_e32 v38, 0
	v_mov_b32_e32 v39, v131
	v_mov_b32_e32 v40, v131
	v_mov_b32_e32 v41, v131
	v_mov_b32_e32 v42, 0
	v_mov_b32_e32 v43, v131
	v_mov_b32_e32 v44, v131
	v_mov_b32_e32 v45, v131
	v_mov_b32_e32 v46, 0
	v_mov_b32_e32 v47, v131
	v_mov_b32_e32 v48, v131
	v_mov_b32_e32 v49, v131
	v_mov_b32_e32 v50, 0
	v_mov_b32_e32 v51, v131
	v_mov_b32_e32 v75, v131
	v_mov_b32_e32 v76, v131
	v_mov_b32_e32 v77, v131
	v_mov_b32_e32 v78, 0
	v_mov_b32_e32 v79, v131
	v_mov_b32_e32 v80, v131
	v_mov_b32_e32 v81, v131
	v_mov_b32_e32 v82, 0
	v_mov_b32_e32 v83, v131
	v_mov_b32_e32 v84, v131
	v_mov_b32_e32 v85, v131
	v_mov_b32_e32 v86, 0
	v_mov_b32_e32 v87, v131
	v_mov_b32_e32 v88, v131
	v_mov_b32_e32 v89, v131
	v_mov_b32_e32 v90, 0
	v_mov_b32_e32 v91, v131
	v_mov_b32_e32 v92, v131
	v_mov_b32_e32 v93, v131
	v_mov_b32_e32 v94, 0
	v_mov_b32_e32 v95, v131
	v_mov_b32_e32 v96, v131
	v_mov_b32_e32 v97, v131
	v_mov_b32_e32 v98, 0
	v_mov_b32_e32 v99, v131
	v_mov_b32_e32 v100, v131
	v_mov_b32_e32 v101, v131
	v_mov_b32_e32 v102, 0
	v_mov_b32_e32 v103, v131
	v_mov_b32_e32 v104, v131
	v_mov_b32_e32 v105, v131
	v_mov_b32_e32 v106, 0
	v_mov_b32_e32 v107, v131
	v_mov_b32_e32 v108, v131
	v_mov_b32_e32 v109, v131
	v_mov_b32_e32 v110, 0
	v_mov_b32_e32 v111, v131
	v_mov_b32_e32 v112, v131
	v_mov_b32_e32 v113, v131
	v_mov_b32_e32 v114, 0
	v_mov_b32_e32 v115, v131
	v_mov_b32_e32 v116, v131
	v_mov_b32_e32 v117, v131
	v_mov_b32_e32 v118, 0
	v_mov_b32_e32 v119, v131
	v_mov_b32_e32 v120, v131
	v_mov_b32_e32 v121, v131
	v_mov_b32_e32 v122, 0
	v_mov_b32_e32 v123, v131
	v_mov_b32_e32 v124, v131
	v_mov_b32_e32 v125, v131
	v_mov_b32_e32 v126, 0
	v_mov_b32_e32 v127, v131
	v_mov_b32_e32 v128, v131
	v_mov_b32_e32 v129, v131
	s_waitcnt lgkmcnt(0)
	s_barrier
.LBB0_750:
	v_lshl_add_u64 v[150:151], v[142:143], 0, s[0:1]
	v_add_co_u32_e32 v152, vcc, s12, v150
	s_and_b32 s24, s23, 1
	s_nop 0
	v_addc_co_u32_e32 v153, vcc, 0, v151, vcc
	v_add_co_u32_e32 v154, vcc, s13, v150
	s_mul_i32 s25, s24, 0x8000
	s_nop 0
	v_addc_co_u32_e32 v155, vcc, 0, v151, vcc
	v_add_co_u32_e32 v158, vcc, s14, v150
	v_add_u32_e32 v199, s25, v147
	v_add_u32_e32 v219, s25, v217
	s_nop 0
	v_addc_co_u32_e32 v159, vcc, 0, v151, vcc
	v_add_co_u32_e32 v162, vcc, s15, v150
	v_add_u32_e32 v198, s25, v146
	v_add_u32_e32 v218, s25, v216
	s_nop 0
	v_addc_co_u32_e32 v163, vcc, 0, v151, vcc
	global_load_dwordx4 v[150:153], v[152:153], off offset:128
	s_nop 0
	global_load_dwordx4 v[154:157], v[154:155], off offset:128
	s_nop 0
	global_load_dwordx4 v[158:161], v[158:159], off offset:128
	s_nop 0
	global_load_dwordx4 v[162:165], v[162:163], off offset:128
	ds_read_b128 v[166:169], v199
	ds_read_b128 v[170:173], v199 offset:2048
	ds_read_b128 v[174:177], v199 offset:4096
	ds_read_b128 v[178:181], v199 offset:6144
	ds_read_b128 v[182:185], v198
	ds_read_b128 v[186:189], v198 offset:2048
	ds_read_b128 v[190:193], v198 offset:4096
	ds_read_b128 v[194:197], v198 offset:6144
	s_add_i32 s23, s23, 1
	s_setprio 1
	s_waitcnt lgkmcnt(3)
	v_mfma_f32_16x16x32_bf16 v[126:129], v[166:169], v[182:185], v[126:129]
	v_mfma_f32_16x16x32_bf16 v[122:125], v[170:173], v[182:185], v[122:125]
	v_mfma_f32_16x16x32_bf16 v[118:121], v[174:177], v[182:185], v[118:121]
	v_mfma_f32_16x16x32_bf16 v[114:117], v[178:181], v[182:185], v[114:117]
	s_waitcnt lgkmcnt(2)
	v_mfma_f32_16x16x32_bf16 v[110:113], v[166:169], v[186:189], v[110:113]
	v_mfma_f32_16x16x32_bf16 v[106:109], v[170:173], v[186:189], v[106:109]
	v_mfma_f32_16x16x32_bf16 v[102:105], v[174:177], v[186:189], v[102:105]
	v_mfma_f32_16x16x32_bf16 v[98:101], v[178:181], v[186:189], v[98:101]
	s_waitcnt lgkmcnt(1)
	v_mfma_f32_16x16x32_bf16 v[94:97], v[166:169], v[190:193], v[94:97]
	v_mfma_f32_16x16x32_bf16 v[90:93], v[170:173], v[190:193], v[90:93]
	v_mfma_f32_16x16x32_bf16 v[86:89], v[174:177], v[190:193], v[86:89]
	v_mfma_f32_16x16x32_bf16 v[82:85], v[178:181], v[190:193], v[82:85]
	s_waitcnt lgkmcnt(0)
	v_mfma_f32_16x16x32_bf16 v[78:81], v[166:169], v[194:197], v[78:81]
	v_mfma_f32_16x16x32_bf16 v[74:77], v[170:173], v[194:197], v[74:77]
	v_mfma_f32_16x16x32_bf16 v[70:73], v[174:177], v[194:197], v[70:73]
	v_mfma_f32_16x16x32_bf16 v[66:69], v[178:181], v[194:197], v[66:69]
	s_setprio 0
	ds_read_b128 v[182:185], v198 offset:8192
	ds_read_b128 v[186:189], v198 offset:10240
	ds_read_b128 v[190:193], v198 offset:12288
	ds_read_b128 v[194:197], v198 offset:14336
	s_setprio 1
	s_waitcnt lgkmcnt(3)
	v_mfma_f32_16x16x32_bf16 v[62:65], v[166:169], v[182:185], v[62:65]
	v_mfma_f32_16x16x32_bf16 v[58:61], v[170:173], v[182:185], v[58:61]
	v_mfma_f32_16x16x32_bf16 v[54:57], v[174:177], v[182:185], v[54:57]
	v_mfma_f32_16x16x32_bf16 v[50:53], v[178:181], v[182:185], v[50:53]
	s_waitcnt lgkmcnt(2)
	v_mfma_f32_16x16x32_bf16 v[46:49], v[166:169], v[186:189], v[46:49]
	v_mfma_f32_16x16x32_bf16 v[42:45], v[170:173], v[186:189], v[42:45]
	v_mfma_f32_16x16x32_bf16 v[38:41], v[174:177], v[186:189], v[38:41]
	v_mfma_f32_16x16x32_bf16 v[34:37], v[178:181], v[186:189], v[34:37]
	s_waitcnt lgkmcnt(1)
	v_mfma_f32_16x16x32_bf16 v[30:33], v[166:169], v[190:193], v[30:33]
	v_mfma_f32_16x16x32_bf16 v[26:29], v[170:173], v[190:193], v[26:29]
	v_mfma_f32_16x16x32_bf16 v[22:25], v[174:177], v[190:193], v[22:25]
	v_mfma_f32_16x16x32_bf16 v[18:21], v[178:181], v[190:193], v[18:21]
	s_waitcnt lgkmcnt(0)
	v_mfma_f32_16x16x32_bf16 v[14:17], v[166:169], v[194:197], v[14:17]
	v_mfma_f32_16x16x32_bf16 v[10:13], v[170:173], v[194:197], v[10:13]
	v_mfma_f32_16x16x32_bf16 v[6:9], v[174:177], v[194:197], v[6:9]
	v_mfma_f32_16x16x32_bf16 v[2:5], v[178:181], v[194:197], v[2:5]
	s_setprio 0
	v_lshl_add_u64 v[174:175], v[140:141], 0, s[0:1]
	v_add_co_u32_e32 v166, vcc, s16, v174
	s_lshl_b32 s24, s24, 8
	s_nop 0
	v_addc_co_u32_e32 v167, vcc, 0, v175, vcc
	v_add_co_u32_e32 v170, vcc, s17, v174
	s_xor_b32 s24, s24, 0x100
	s_nop 0
	v_addc_co_u32_e32 v171, vcc, 0, v175, vcc
	v_add_co_u32_e32 v176, vcc, s18, v174
	global_load_dwordx4 v[166:169], v[166:167], off offset:128
	s_nop 0
	global_load_dwordx4 v[170:173], v[170:171], off offset:128
	v_addc_co_u32_e32 v177, vcc, 0, v175, vcc
	v_add_co_u32_e32 v178, vcc, s19, v174
	s_mulk_i32 s24, 0x80
	s_nop 0
	v_addc_co_u32_e32 v179, vcc, 0, v175, vcc
	global_load_dwordx4 v[174:177], v[176:177], off offset:128
	s_nop 0
	global_load_dwordx4 v[178:181], v[178:179], off offset:128
	v_add_u32_e32 v182, s24, v144
	s_waitcnt vmcnt(7)
	ds_write_b128 v182, v[150:153]
	s_waitcnt vmcnt(6)
	ds_write_b128 v182, v[154:157] offset:8192
	s_waitcnt vmcnt(5)
	ds_write_b128 v182, v[158:161] offset:16384
	s_waitcnt vmcnt(4)
	ds_write_b128 v182, v[162:165] offset:24576
	ds_read_b128 v[150:153], v219
	ds_read_b128 v[154:157], v219 offset:2048
	ds_read_b128 v[158:161], v219 offset:4096
	ds_read_b128 v[162:165], v219 offset:6144
	ds_read_b128 v[182:185], v218
	ds_read_b128 v[186:189], v218 offset:2048
	ds_read_b128 v[190:193], v218 offset:4096
	ds_read_b128 v[194:197], v218 offset:6144
	s_setprio 1
	s_waitcnt lgkmcnt(3)
	v_mfma_f32_16x16x32_bf16 v[126:129], v[150:153], v[182:185], v[126:129]
	v_mfma_f32_16x16x32_bf16 v[122:125], v[154:157], v[182:185], v[122:125]
	v_mfma_f32_16x16x32_bf16 v[118:121], v[158:161], v[182:185], v[118:121]
	v_mfma_f32_16x16x32_bf16 v[114:117], v[162:165], v[182:185], v[114:117]
	s_waitcnt lgkmcnt(2)
	v_mfma_f32_16x16x32_bf16 v[110:113], v[150:153], v[186:189], v[110:113]
	v_mfma_f32_16x16x32_bf16 v[106:109], v[154:157], v[186:189], v[106:109]
	v_mfma_f32_16x16x32_bf16 v[102:105], v[158:161], v[186:189], v[102:105]
	v_mfma_f32_16x16x32_bf16 v[98:101], v[162:165], v[186:189], v[98:101]
	s_waitcnt lgkmcnt(1)
	v_mfma_f32_16x16x32_bf16 v[94:97], v[150:153], v[190:193], v[94:97]
	v_mfma_f32_16x16x32_bf16 v[90:93], v[154:157], v[190:193], v[90:93]
	v_mfma_f32_16x16x32_bf16 v[86:89], v[158:161], v[190:193], v[86:89]
	v_mfma_f32_16x16x32_bf16 v[82:85], v[162:165], v[190:193], v[82:85]
	s_waitcnt lgkmcnt(0)
	v_mfma_f32_16x16x32_bf16 v[78:81], v[150:153], v[194:197], v[78:81]
	v_mfma_f32_16x16x32_bf16 v[74:77], v[154:157], v[194:197], v[74:77]
	v_mfma_f32_16x16x32_bf16 v[70:73], v[158:161], v[194:197], v[70:73]
	v_mfma_f32_16x16x32_bf16 v[66:69], v[162:165], v[194:197], v[66:69]
	s_setprio 0
	ds_read_b128 v[182:185], v218 offset:8192
	ds_read_b128 v[186:189], v218 offset:10240
	ds_read_b128 v[190:193], v218 offset:12288
	ds_read_b128 v[194:197], v218 offset:14336
	s_setprio 1
	s_waitcnt lgkmcnt(3)
	v_mfma_f32_16x16x32_bf16 v[62:65], v[150:153], v[182:185], v[62:65]
	v_mfma_f32_16x16x32_bf16 v[58:61], v[154:157], v[182:185], v[58:61]
	v_mfma_f32_16x16x32_bf16 v[54:57], v[158:161], v[182:185], v[54:57]
	v_mfma_f32_16x16x32_bf16 v[50:53], v[162:165], v[182:185], v[50:53]
	s_waitcnt lgkmcnt(2)
	v_mfma_f32_16x16x32_bf16 v[46:49], v[150:153], v[186:189], v[46:49]
	v_mfma_f32_16x16x32_bf16 v[42:45], v[154:157], v[186:189], v[42:45]
	v_mfma_f32_16x16x32_bf16 v[38:41], v[158:161], v[186:189], v[38:41]
	v_mfma_f32_16x16x32_bf16 v[34:37], v[162:165], v[186:189], v[34:37]
	s_waitcnt lgkmcnt(1)
	v_mfma_f32_16x16x32_bf16 v[30:33], v[150:153], v[190:193], v[30:33]
	v_mfma_f32_16x16x32_bf16 v[26:29], v[154:157], v[190:193], v[26:29]
	v_mfma_f32_16x16x32_bf16 v[22:25], v[158:161], v[190:193], v[22:25]
	v_mfma_f32_16x16x32_bf16 v[18:21], v[162:165], v[190:193], v[18:21]
	s_waitcnt lgkmcnt(0)
	v_mfma_f32_16x16x32_bf16 v[14:17], v[150:153], v[194:197], v[14:17]
	v_mfma_f32_16x16x32_bf16 v[10:13], v[154:157], v[194:197], v[10:13]
	v_mfma_f32_16x16x32_bf16 v[6:9], v[158:161], v[194:197], v[6:9]
	v_mfma_f32_16x16x32_bf16 v[2:5], v[162:165], v[194:197], v[2:5]
	s_setprio 0
	s_add_u32 s0, s0, 0x80
	s_addc_u32 s1, s1, 0
	v_add_u32_e32 v150, s24, v145
	s_cmpk_eq_i32 s0, 0x780
	s_waitcnt vmcnt(3)
	ds_write_b128 v150, v[166:169]
	s_waitcnt vmcnt(2)
	ds_write_b128 v150, v[170:173] offset:8192
	s_waitcnt vmcnt(1)
	ds_write_b128 v150, v[174:177] offset:16384
	s_waitcnt vmcnt(0)
	ds_write_b128 v150, v[178:181] offset:24576
	s_waitcnt lgkmcnt(0)
	s_barrier
	s_cbranch_scc0 .LBB0_750
	ds_read_b128 v[140:143], v147 offset:32768
	ds_read_b128 v[150:153], v147 offset:34816
	ds_read_b128 v[154:157], v147 offset:36864
	ds_read_b128 v[158:161], v147 offset:38912
	ds_read_b128 v[162:165], v146 offset:32768
	ds_read_b128 v[166:169], v146 offset:34816
	ds_read_b128 v[170:173], v146 offset:36864
	ds_read_b128 v[174:177], v146 offset:38912
	s_setprio 1
	s_waitcnt lgkmcnt(3)
	v_mfma_f32_16x16x32_bf16 v[126:129], v[140:143], v[162:165], v[126:129]
	v_mfma_f32_16x16x32_bf16 v[122:125], v[150:153], v[162:165], v[122:125]
	v_mfma_f32_16x16x32_bf16 v[118:121], v[154:157], v[162:165], v[118:121]
	v_mfma_f32_16x16x32_bf16 v[114:117], v[158:161], v[162:165], v[114:117]
	s_waitcnt lgkmcnt(2)
	v_mfma_f32_16x16x32_bf16 v[110:113], v[140:143], v[166:169], v[110:113]
	v_mfma_f32_16x16x32_bf16 v[106:109], v[150:153], v[166:169], v[106:109]
	v_mfma_f32_16x16x32_bf16 v[102:105], v[154:157], v[166:169], v[102:105]
	v_mfma_f32_16x16x32_bf16 v[98:101], v[158:161], v[166:169], v[98:101]
	s_waitcnt lgkmcnt(1)
	v_mfma_f32_16x16x32_bf16 v[94:97], v[140:143], v[170:173], v[94:97]
	v_mfma_f32_16x16x32_bf16 v[90:93], v[150:153], v[170:173], v[90:93]
	v_mfma_f32_16x16x32_bf16 v[86:89], v[154:157], v[170:173], v[86:89]
	v_mfma_f32_16x16x32_bf16 v[82:85], v[158:161], v[170:173], v[82:85]
	s_waitcnt lgkmcnt(0)
	v_mfma_f32_16x16x32_bf16 v[78:81], v[140:143], v[174:177], v[78:81]
	v_mfma_f32_16x16x32_bf16 v[74:77], v[150:153], v[174:177], v[74:77]
	v_mfma_f32_16x16x32_bf16 v[70:73], v[154:157], v[174:177], v[70:73]
	v_mfma_f32_16x16x32_bf16 v[66:69], v[158:161], v[174:177], v[66:69]
	s_setprio 0
	ds_read_b128 v[162:165], v146 offset:40960
	ds_read_b128 v[166:169], v146 offset:43008
	ds_read_b128 v[170:173], v146 offset:45056
	ds_read_b128 v[174:177], v146 offset:47104
	s_setprio 1
	s_waitcnt lgkmcnt(3)
	v_mfma_f32_16x16x32_bf16 v[62:65], v[140:143], v[162:165], v[62:65]
	v_mfma_f32_16x16x32_bf16 v[58:61], v[150:153], v[162:165], v[58:61]
	v_mfma_f32_16x16x32_bf16 v[54:57], v[154:157], v[162:165], v[54:57]
	v_mfma_f32_16x16x32_bf16 v[50:53], v[158:161], v[162:165], v[50:53]
	s_waitcnt lgkmcnt(2)
	v_mfma_f32_16x16x32_bf16 v[46:49], v[140:143], v[166:169], v[46:49]
	v_mfma_f32_16x16x32_bf16 v[42:45], v[150:153], v[166:169], v[42:45]
	v_mfma_f32_16x16x32_bf16 v[38:41], v[154:157], v[166:169], v[38:41]
	v_mfma_f32_16x16x32_bf16 v[34:37], v[158:161], v[166:169], v[34:37]
	s_waitcnt lgkmcnt(1)
	v_mfma_f32_16x16x32_bf16 v[30:33], v[140:143], v[170:173], v[30:33]
	v_mfma_f32_16x16x32_bf16 v[26:29], v[150:153], v[170:173], v[26:29]
	v_mfma_f32_16x16x32_bf16 v[22:25], v[154:157], v[170:173], v[22:25]
	v_mfma_f32_16x16x32_bf16 v[18:21], v[158:161], v[170:173], v[18:21]
	s_waitcnt lgkmcnt(0)
	v_mfma_f32_16x16x32_bf16 v[14:17], v[140:143], v[174:177], v[14:17]
	v_mfma_f32_16x16x32_bf16 v[10:13], v[150:153], v[174:177], v[10:13]
	v_mfma_f32_16x16x32_bf16 v[6:9], v[154:157], v[174:177], v[6:9]
	v_mfma_f32_16x16x32_bf16 v[2:5], v[158:161], v[174:177], v[2:5]
	s_setprio 0
	ds_read_b128 v[140:143], v217 offset:32768
	ds_read_b128 v[150:153], v217 offset:34816
	ds_read_b128 v[154:157], v217 offset:36864
	ds_read_b128 v[158:161], v217 offset:38912
	ds_read_b128 v[162:165], v216 offset:32768
	ds_read_b128 v[166:169], v216 offset:34816
	ds_read_b128 v[170:173], v216 offset:36864
	ds_read_b128 v[174:177], v216 offset:38912
	s_setprio 1
	s_waitcnt lgkmcnt(3)
	v_mfma_f32_16x16x32_bf16 v[126:129], v[140:143], v[162:165], v[126:129]
	v_mfma_f32_16x16x32_bf16 v[122:125], v[150:153], v[162:165], v[122:125]
	v_mfma_f32_16x16x32_bf16 v[118:121], v[154:157], v[162:165], v[118:121]
	v_mfma_f32_16x16x32_bf16 v[114:117], v[158:161], v[162:165], v[114:117]
	s_waitcnt lgkmcnt(2)
	v_mfma_f32_16x16x32_bf16 v[110:113], v[140:143], v[166:169], v[110:113]
	v_mfma_f32_16x16x32_bf16 v[106:109], v[150:153], v[166:169], v[106:109]
	v_mfma_f32_16x16x32_bf16 v[102:105], v[154:157], v[166:169], v[102:105]
	v_mfma_f32_16x16x32_bf16 v[98:101], v[158:161], v[166:169], v[98:101]
	s_waitcnt lgkmcnt(1)
	v_mfma_f32_16x16x32_bf16 v[94:97], v[140:143], v[170:173], v[94:97]
	v_mfma_f32_16x16x32_bf16 v[162:165], v[150:153], v[170:173], v[90:93]
	v_mfma_f32_16x16x32_bf16 v[86:89], v[154:157], v[170:173], v[86:89]
	v_mfma_f32_16x16x32_bf16 v[82:85], v[158:161], v[170:173], v[82:85]
	s_waitcnt lgkmcnt(0)
	v_mfma_f32_16x16x32_bf16 v[78:81], v[140:143], v[174:177], v[78:81]
	v_mfma_f32_16x16x32_bf16 v[74:77], v[150:153], v[174:177], v[74:77]
	v_mfma_f32_16x16x32_bf16 v[70:73], v[154:157], v[174:177], v[70:73]
	v_mfma_f32_16x16x32_bf16 v[66:69], v[158:161], v[174:177], v[66:69]
	s_setprio 0
	ds_read_b128 v[90:93], v216 offset:40960
	ds_read_b128 v[166:169], v216 offset:43008
	ds_read_b128 v[170:173], v216 offset:45056
	ds_read_b128 v[174:177], v216 offset:47104
	s_setprio 1
	s_waitcnt lgkmcnt(3)
	v_mfma_f32_16x16x32_bf16 v[62:65], v[140:143], v[90:93], v[62:65]
	v_mfma_f32_16x16x32_bf16 v[58:61], v[150:153], v[90:93], v[58:61]
	v_mfma_f32_16x16x32_bf16 v[54:57], v[154:157], v[90:93], v[54:57]
	v_mfma_f32_16x16x32_bf16 v[50:53], v[158:161], v[90:93], v[50:53]
	s_waitcnt lgkmcnt(2)
	v_mfma_f32_16x16x32_bf16 v[46:49], v[140:143], v[166:169], v[46:49]
	v_mfma_f32_16x16x32_bf16 v[42:45], v[150:153], v[166:169], v[42:45]
	v_mfma_f32_16x16x32_bf16 v[38:41], v[154:157], v[166:169], v[38:41]
	v_mfma_f32_16x16x32_bf16 v[34:37], v[158:161], v[166:169], v[34:37]
	s_waitcnt lgkmcnt(1)
	v_mfma_f32_16x16x32_bf16 v[30:33], v[140:143], v[170:173], v[30:33]
	v_mfma_f32_16x16x32_bf16 v[26:29], v[150:153], v[170:173], v[26:29]
	v_mfma_f32_16x16x32_bf16 v[22:25], v[154:157], v[170:173], v[22:25]
	v_mfma_f32_16x16x32_bf16 v[18:21], v[158:161], v[170:173], v[18:21]
	s_waitcnt lgkmcnt(0)
	v_mfma_f32_16x16x32_bf16 v[14:17], v[140:143], v[174:177], v[14:17]
	v_mfma_f32_16x16x32_bf16 v[10:13], v[150:153], v[174:177], v[10:13]
	v_mfma_f32_16x16x32_bf16 v[6:9], v[154:157], v[174:177], v[6:9]
	v_mfma_f32_16x16x32_bf16 v[2:5], v[158:161], v[174:177], v[2:5]
	s_setprio 0
	v_mul_f32_e32 v93, 0xbfb8aa3b, v126
	v_exp_f32_e32 v93, v93
	v_mul_f32_e32 v140, 0xbfb8aa3b, v127
	v_exp_f32_e32 v141, v140
	v_or_b32_e32 v90, s22, v148
	v_add_f32_e32 v93, 1.0, v93
	v_rcp_f32_e32 v140, v93
	v_add_f32_e32 v93, 1.0, v141
	v_mul_f32_e32 v141, 0xbfb8aa3b, v128
	v_exp_f32_e32 v142, v141
	v_mul_f32_e32 v141, 0xbfb8aa3b, v129
	v_exp_f32_e32 v143, v141
	v_rcp_f32_e32 v141, v93
	v_add_f32_e32 v93, 1.0, v142
	v_rcp_f32_e32 v142, v93
	v_add_f32_e32 v93, 1.0, v143
	v_rcp_f32_e32 v143, v93
	v_pk_mul_f32 v[126:127], v[126:127], v[140:141]
	v_mul_f32_e32 v93, 0xbfb8aa3b, v118
	v_pk_mul_f32 v[122:123], v[122:123], v[126:127]
	v_pk_mul_f32 v[126:127], v[128:129], v[142:143]
	v_cvt_pk_bf16_f32 v122, v122, v123
	v_exp_f32_e32 v93, v93
	v_mul_f32_e32 v123, 0xbfb8aa3b, v119
	v_pk_mul_f32 v[124:125], v[124:125], v[126:127]
	v_exp_f32_e32 v126, v123
	v_cvt_pk_bf16_f32 v123, v124, v125
	v_add_f32_e32 v93, 1.0, v93
	v_mul_f32_e32 v125, 0xbfb8aa3b, v120
	v_rcp_f32_e32 v124, v93
	v_add_f32_e32 v93, 1.0, v126
	v_exp_f32_e32 v126, v125
	v_mul_f32_e32 v125, 0xbfb8aa3b, v121
	v_exp_f32_e32 v127, v125
	v_rcp_f32_e32 v125, v93
	v_add_f32_e32 v93, 1.0, v126
	v_rcp_f32_e32 v126, v93
	v_add_f32_e32 v93, 1.0, v127
	v_rcp_f32_e32 v127, v93
	v_ashrrev_i32_e32 v90, 1, v90
	v_pk_mul_f32 v[118:119], v[118:119], v[124:125]
	v_ashrrev_i32_e32 v91, 31, v90
	v_pk_mul_f32 v[114:115], v[114:115], v[118:119]
	v_pk_mul_f32 v[118:119], v[120:121], v[126:127]
	v_add_u32_e32 v92, s21, v149
	v_lshl_add_u64 v[90:91], v[90:91], 1, v[136:137]
	v_pk_mul_f32 v[116:117], v[116:117], v[118:119]
	v_mad_i64_i32 v[150:151], s[0:1], v92, s20, v[90:91]
	v_cvt_pk_bf16_f32 v114, v114, v115
	v_cvt_pk_bf16_f32 v115, v116, v117
	v_mul_f32_e32 v93, 0xbfb8aa3b, v110
	s_barrier
	global_store_dwordx2 v[150:151], v[114:115], off offset:32
	v_exp_f32_e32 v93, v93
	v_mul_f32_e32 v114, 0xbfb8aa3b, v111
	v_exp_f32_e32 v115, v114
	v_or_b32_e32 v118, 16, v92
	v_add_f32_e32 v93, 1.0, v93
	v_rcp_f32_e32 v114, v93
	v_add_f32_e32 v93, 1.0, v115
	v_mul_f32_e32 v115, 0xbfb8aa3b, v112
	v_exp_f32_e32 v116, v115
	v_mul_f32_e32 v115, 0xbfb8aa3b, v113
	v_exp_f32_e32 v117, v115
	v_rcp_f32_e32 v115, v93
	v_add_f32_e32 v93, 1.0, v116
	v_rcp_f32_e32 v116, v93
	v_add_f32_e32 v93, 1.0, v117
	v_rcp_f32_e32 v117, v93
	v_pk_mul_f32 v[110:111], v[110:111], v[114:115]
	v_mul_f32_e32 v93, 0xbfb8aa3b, v102
	v_pk_mul_f32 v[106:107], v[106:107], v[110:111]
	v_pk_mul_f32 v[110:111], v[112:113], v[116:117]
	v_cvt_pk_bf16_f32 v106, v106, v107
	v_exp_f32_e32 v93, v93
	v_mul_f32_e32 v107, 0xbfb8aa3b, v103
	v_pk_mul_f32 v[108:109], v[108:109], v[110:111]
	v_exp_f32_e32 v110, v107
	v_cvt_pk_bf16_f32 v107, v108, v109
	v_add_f32_e32 v93, 1.0, v93
	v_mul_f32_e32 v109, 0xbfb8aa3b, v104
	v_rcp_f32_e32 v108, v93
	v_add_f32_e32 v93, 1.0, v110
	v_exp_f32_e32 v110, v109
	v_mul_f32_e32 v109, 0xbfb8aa3b, v105
	v_exp_f32_e32 v111, v109
	v_rcp_f32_e32 v109, v93
	v_add_f32_e32 v93, 1.0, v110
	v_rcp_f32_e32 v110, v93
	v_add_f32_e32 v93, 1.0, v111
	v_rcp_f32_e32 v111, v93
	v_pk_mul_f32 v[102:103], v[102:103], v[108:109]
	v_mad_i64_i32 v[118:119], s[0:1], v118, s20, v[90:91]
	v_pk_mul_f32 v[98:99], v[98:99], v[102:103]
	v_pk_mul_f32 v[102:103], v[104:105], v[110:111]
	v_cvt_pk_bf16_f32 v98, v98, v99
	v_pk_mul_f32 v[100:101], v[100:101], v[102:103]
	v_mul_f32_e32 v93, 0xbfb8aa3b, v94
	v_cvt_pk_bf16_f32 v99, v100, v101
	global_store_dwordx2 v[118:119], v[98:99], off offset:32
	v_exp_f32_e32 v93, v93
	v_mul_f32_e32 v98, 0xbfb8aa3b, v95
	v_exp_f32_e32 v99, v98
	v_or_b32_e32 v102, 32, v92
	v_add_f32_e32 v93, 1.0, v93
	v_rcp_f32_e32 v98, v93
	v_add_f32_e32 v93, 1.0, v99
	v_mul_f32_e32 v99, 0xbfb8aa3b, v96
	v_exp_f32_e32 v100, v99
	v_mul_f32_e32 v99, 0xbfb8aa3b, v97
	v_exp_f32_e32 v101, v99
	v_rcp_f32_e32 v99, v93
	v_add_f32_e32 v93, 1.0, v100
	v_rcp_f32_e32 v100, v93
	v_add_f32_e32 v93, 1.0, v101
	v_rcp_f32_e32 v101, v93
	v_pk_mul_f32 v[94:95], v[94:95], v[98:99]
	v_mul_f32_e32 v93, 0xbfb8aa3b, v86
	v_pk_mul_f32 v[94:95], v[162:163], v[94:95]
	v_exp_f32_e32 v93, v93
	v_cvt_pk_bf16_f32 v94, v94, v95
	v_mul_f32_e32 v95, 0xbfb8aa3b, v87
	v_exp_f32_e32 v98, v95
	v_pk_mul_f32 v[96:97], v[96:97], v[100:101]
	v_add_f32_e32 v93, 1.0, v93
	v_pk_mul_f32 v[96:97], v[164:165], v[96:97]
	v_mad_i64_i32 v[102:103], s[0:1], v102, s20, v[90:91]
	v_cvt_pk_bf16_f32 v95, v96, v97
	v_mul_f32_e32 v97, 0xbfb8aa3b, v88
	v_rcp_f32_e32 v96, v93
	v_add_f32_e32 v93, 1.0, v98
	v_exp_f32_e32 v98, v97
	v_mul_f32_e32 v97, 0xbfb8aa3b, v89
	v_exp_f32_e32 v99, v97
	v_rcp_f32_e32 v97, v93
	v_add_f32_e32 v93, 1.0, v98
	v_rcp_f32_e32 v98, v93
	v_add_f32_e32 v93, 1.0, v99
	v_rcp_f32_e32 v99, v93
	v_pk_mul_f32 v[86:87], v[86:87], v[96:97]
	s_add_i32 s3, s3, s7
	v_pk_mul_f32 v[82:83], v[82:83], v[86:87]
	v_pk_mul_f32 v[86:87], v[88:89], v[98:99]
	v_cvt_pk_bf16_f32 v82, v82, v83
	v_pk_mul_f32 v[84:85], v[84:85], v[86:87]
	v_or_b32_e32 v86, 48, v92
	v_cvt_pk_bf16_f32 v83, v84, v85
	global_store_dwordx2 v[102:103], v[82:83], off offset:32
	v_mul_f32_e32 v82, 0xbfb8aa3b, v78
	v_mul_f32_e32 v83, 0xbfb8aa3b, v79
	v_exp_f32_e32 v82, v82
	v_exp_f32_e32 v83, v83
	v_mul_f32_e32 v84, 0xbfb8aa3b, v80
	v_mul_f32_e32 v85, 0xbfb8aa3b, v81
	v_exp_f32_e32 v84, v84
	v_exp_f32_e32 v85, v85
	v_add_f32_e32 v82, 1.0, v82
	v_add_f32_e32 v83, 1.0, v83
	v_rcp_f32_e32 v82, v82
	v_rcp_f32_e32 v83, v83
	v_add_f32_e32 v84, 1.0, v84
	v_add_f32_e32 v85, 1.0, v85
	v_rcp_f32_e32 v84, v84
	v_rcp_f32_e32 v85, v85
	v_pk_mul_f32 v[78:79], v[78:79], v[82:83]
	v_mad_i64_i32 v[86:87], s[0:1], v86, s20, v[90:91]
	v_pk_mul_f32 v[74:75], v[74:75], v[78:79]
	v_pk_mul_f32 v[78:79], v[80:81], v[84:85]
	v_cvt_pk_bf16_f32 v74, v74, v75
	v_mul_f32_e32 v75, 0xbfb8aa3b, v70
	v_pk_mul_f32 v[76:77], v[76:77], v[78:79]
	v_exp_f32_e32 v78, v75
	v_mul_f32_e32 v75, 0xbfb8aa3b, v71
	v_exp_f32_e32 v79, v75
	v_cvt_pk_bf16_f32 v75, v76, v77
	v_add_f32_e32 v76, 1.0, v78
	v_mul_f32_e32 v78, 0xbfb8aa3b, v72
	v_add_f32_e32 v77, 1.0, v79
	v_mul_f32_e32 v79, 0xbfb8aa3b, v73
	v_exp_f32_e32 v78, v78
	v_exp_f32_e32 v79, v79
	v_rcp_f32_e32 v76, v76
	v_rcp_f32_e32 v77, v77
	v_add_f32_e32 v78, 1.0, v78
	v_add_f32_e32 v79, 1.0, v79
	v_rcp_f32_e32 v78, v78
	v_rcp_f32_e32 v79, v79
	v_pk_mul_f32 v[70:71], v[70:71], v[76:77]
	s_cmpk_gt_i32 s3, 0x2bf
	v_pk_mul_f32 v[66:67], v[66:67], v[70:71]
	v_pk_mul_f32 v[70:71], v[72:73], v[78:79]
	v_cvt_pk_bf16_f32 v66, v66, v67
	v_pk_mul_f32 v[68:69], v[68:69], v[70:71]
	v_or_b32_e32 v70, 64, v92
	v_cvt_pk_bf16_f32 v67, v68, v69
	global_store_dwordx2 v[86:87], v[66:67], off offset:32
	v_mul_f32_e32 v66, 0xbfb8aa3b, v62
	v_mul_f32_e32 v67, 0xbfb8aa3b, v63
	v_exp_f32_e32 v66, v66
	v_exp_f32_e32 v67, v67
	v_mul_f32_e32 v68, 0xbfb8aa3b, v64
	v_mul_f32_e32 v69, 0xbfb8aa3b, v65
	v_exp_f32_e32 v68, v68
	v_exp_f32_e32 v69, v69
	v_add_f32_e32 v66, 1.0, v66
	v_add_f32_e32 v67, 1.0, v67
	v_rcp_f32_e32 v66, v66
	v_rcp_f32_e32 v67, v67
	v_add_f32_e32 v68, 1.0, v68
	v_add_f32_e32 v69, 1.0, v69
	v_rcp_f32_e32 v68, v68
	v_rcp_f32_e32 v69, v69
	v_pk_mul_f32 v[62:63], v[62:63], v[66:67]
	v_mad_i64_i32 v[70:71], s[0:1], v70, s20, v[90:91]
	v_pk_mul_f32 v[58:59], v[58:59], v[62:63]
	v_pk_mul_f32 v[62:63], v[64:65], v[68:69]
	v_cvt_pk_bf16_f32 v58, v58, v59
	v_mul_f32_e32 v59, 0xbfb8aa3b, v54
	v_pk_mul_f32 v[60:61], v[60:61], v[62:63]
	v_exp_f32_e32 v62, v59
	v_mul_f32_e32 v59, 0xbfb8aa3b, v55
	v_exp_f32_e32 v63, v59
	v_cvt_pk_bf16_f32 v59, v60, v61
	v_add_f32_e32 v60, 1.0, v62
	v_mul_f32_e32 v62, 0xbfb8aa3b, v56
	v_add_f32_e32 v61, 1.0, v63
	v_mul_f32_e32 v63, 0xbfb8aa3b, v57
	v_exp_f32_e32 v62, v62
	v_exp_f32_e32 v63, v63
	v_rcp_f32_e32 v60, v60
	v_rcp_f32_e32 v61, v61
	v_add_f32_e32 v62, 1.0, v62
	v_add_f32_e32 v63, 1.0, v63
	v_rcp_f32_e32 v62, v62
	v_rcp_f32_e32 v63, v63
	v_pk_mul_f32 v[54:55], v[54:55], v[60:61]
	v_add_u32_e32 v130, s8, v130
	v_pk_mul_f32 v[50:51], v[50:51], v[54:55]
	v_pk_mul_f32 v[54:55], v[56:57], v[62:63]
	v_cvt_pk_bf16_f32 v50, v50, v51
	v_pk_mul_f32 v[52:53], v[52:53], v[54:55]
	v_or_b32_e32 v54, 0x50, v92
	v_cvt_pk_bf16_f32 v51, v52, v53
	global_store_dwordx2 v[70:71], v[50:51], off offset:32
	v_mul_f32_e32 v50, 0xbfb8aa3b, v46
	v_mul_f32_e32 v51, 0xbfb8aa3b, v47
	v_exp_f32_e32 v50, v50
	v_exp_f32_e32 v51, v51
	v_mul_f32_e32 v52, 0xbfb8aa3b, v48
	v_mul_f32_e32 v53, 0xbfb8aa3b, v49
	v_exp_f32_e32 v52, v52
	v_exp_f32_e32 v53, v53
	v_add_f32_e32 v50, 1.0, v50
	v_add_f32_e32 v51, 1.0, v51
	v_rcp_f32_e32 v50, v50
	v_rcp_f32_e32 v51, v51
	v_add_f32_e32 v52, 1.0, v52
	v_add_f32_e32 v53, 1.0, v53
	v_rcp_f32_e32 v52, v52
	v_rcp_f32_e32 v53, v53
	v_pk_mul_f32 v[46:47], v[46:47], v[50:51]
	v_mad_i64_i32 v[54:55], s[0:1], v54, s20, v[90:91]
	v_pk_mul_f32 v[42:43], v[42:43], v[46:47]
	v_pk_mul_f32 v[46:47], v[48:49], v[52:53]
	v_cvt_pk_bf16_f32 v42, v42, v43
	v_mul_f32_e32 v43, 0xbfb8aa3b, v38
	v_pk_mul_f32 v[44:45], v[44:45], v[46:47]
	v_exp_f32_e32 v46, v43
	v_mul_f32_e32 v43, 0xbfb8aa3b, v39
	v_exp_f32_e32 v47, v43
	v_cvt_pk_bf16_f32 v43, v44, v45
	v_add_f32_e32 v44, 1.0, v46
	v_mul_f32_e32 v46, 0xbfb8aa3b, v40
	v_add_f32_e32 v45, 1.0, v47
	v_mul_f32_e32 v47, 0xbfb8aa3b, v41
	v_exp_f32_e32 v46, v46
	v_exp_f32_e32 v47, v47
	v_rcp_f32_e32 v44, v44
	v_rcp_f32_e32 v45, v45
	v_add_f32_e32 v46, 1.0, v46
	v_add_f32_e32 v47, 1.0, v47
	v_rcp_f32_e32 v46, v46
	v_rcp_f32_e32 v47, v47
	v_pk_mul_f32 v[38:39], v[38:39], v[44:45]
	global_store_dwordx2 v[150:151], v[122:123], off
	v_pk_mul_f32 v[34:35], v[34:35], v[38:39]
	v_pk_mul_f32 v[38:39], v[40:41], v[46:47]
	v_cvt_pk_bf16_f32 v34, v34, v35
	v_pk_mul_f32 v[36:37], v[36:37], v[38:39]
	v_or_b32_e32 v38, 0x60, v92
	v_cvt_pk_bf16_f32 v35, v36, v37
	global_store_dwordx2 v[54:55], v[34:35], off offset:32
	v_mul_f32_e32 v34, 0xbfb8aa3b, v30
	v_mul_f32_e32 v35, 0xbfb8aa3b, v31
	v_exp_f32_e32 v34, v34
	v_exp_f32_e32 v35, v35
	v_mul_f32_e32 v36, 0xbfb8aa3b, v32
	v_mul_f32_e32 v37, 0xbfb8aa3b, v33
	v_exp_f32_e32 v36, v36
	v_exp_f32_e32 v37, v37
	v_add_f32_e32 v34, 1.0, v34
	v_add_f32_e32 v35, 1.0, v35
	v_rcp_f32_e32 v34, v34
	v_rcp_f32_e32 v35, v35
	v_add_f32_e32 v36, 1.0, v36
	v_add_f32_e32 v37, 1.0, v37
	v_rcp_f32_e32 v36, v36
	v_rcp_f32_e32 v37, v37
	v_pk_mul_f32 v[30:31], v[30:31], v[34:35]
	v_mad_i64_i32 v[38:39], s[0:1], v38, s20, v[90:91]
	v_pk_mul_f32 v[26:27], v[26:27], v[30:31]
	v_pk_mul_f32 v[30:31], v[32:33], v[36:37]
	v_cvt_pk_bf16_f32 v26, v26, v27
	v_mul_f32_e32 v27, 0xbfb8aa3b, v22
	v_pk_mul_f32 v[28:29], v[28:29], v[30:31]
	v_exp_f32_e32 v30, v27
	v_mul_f32_e32 v27, 0xbfb8aa3b, v23
	v_exp_f32_e32 v31, v27
	v_cvt_pk_bf16_f32 v27, v28, v29
	v_add_f32_e32 v28, 1.0, v30
	v_mul_f32_e32 v30, 0xbfb8aa3b, v24
	v_add_f32_e32 v29, 1.0, v31
	v_mul_f32_e32 v31, 0xbfb8aa3b, v25
	v_exp_f32_e32 v30, v30
	v_exp_f32_e32 v31, v31
	v_rcp_f32_e32 v28, v28
	v_rcp_f32_e32 v29, v29
	v_add_f32_e32 v30, 1.0, v30
	v_add_f32_e32 v31, 1.0, v31
	v_rcp_f32_e32 v30, v30
	v_rcp_f32_e32 v31, v31
	v_pk_mul_f32 v[22:23], v[22:23], v[28:29]
	global_store_dwordx2 v[118:119], v[106:107], off
	v_pk_mul_f32 v[18:19], v[18:19], v[22:23]
	v_pk_mul_f32 v[22:23], v[24:25], v[30:31]
	v_cvt_pk_bf16_f32 v18, v18, v19
	v_pk_mul_f32 v[20:21], v[20:21], v[22:23]
	v_or_b32_e32 v22, 0x70, v92
	v_cvt_pk_bf16_f32 v19, v20, v21
	global_store_dwordx2 v[38:39], v[18:19], off offset:32
	v_mul_f32_e32 v18, 0xbfb8aa3b, v14
	v_mul_f32_e32 v19, 0xbfb8aa3b, v15
	v_exp_f32_e32 v18, v18
	v_exp_f32_e32 v19, v19
	v_mul_f32_e32 v20, 0xbfb8aa3b, v16
	v_mul_f32_e32 v21, 0xbfb8aa3b, v17
	v_exp_f32_e32 v20, v20
	v_exp_f32_e32 v21, v21
	v_add_f32_e32 v18, 1.0, v18
	v_add_f32_e32 v19, 1.0, v19
	v_rcp_f32_e32 v18, v18
	v_rcp_f32_e32 v19, v19
	v_add_f32_e32 v20, 1.0, v20
	v_add_f32_e32 v21, 1.0, v21
	v_rcp_f32_e32 v20, v20
	v_rcp_f32_e32 v21, v21
	v_pk_mul_f32 v[14:15], v[14:15], v[18:19]
	v_mad_i64_i32 v[22:23], s[0:1], v22, s20, v[90:91]
	v_pk_mul_f32 v[10:11], v[10:11], v[14:15]
	v_pk_mul_f32 v[14:15], v[16:17], v[20:21]
	v_cvt_pk_bf16_f32 v10, v10, v11
	v_mul_f32_e32 v11, 0xbfb8aa3b, v6
	v_pk_mul_f32 v[12:13], v[12:13], v[14:15]
	v_exp_f32_e32 v14, v11
	v_mul_f32_e32 v11, 0xbfb8aa3b, v7
	v_exp_f32_e32 v15, v11
	v_cvt_pk_bf16_f32 v11, v12, v13
	v_add_f32_e32 v12, 1.0, v14
	v_mul_f32_e32 v14, 0xbfb8aa3b, v8
	v_add_f32_e32 v13, 1.0, v15
	v_mul_f32_e32 v15, 0xbfb8aa3b, v9
	v_exp_f32_e32 v14, v14
	v_exp_f32_e32 v15, v15
	v_rcp_f32_e32 v12, v12
	v_rcp_f32_e32 v13, v13
	v_add_f32_e32 v14, 1.0, v14
	v_add_f32_e32 v15, 1.0, v15
	v_rcp_f32_e32 v14, v14
	v_rcp_f32_e32 v15, v15
	v_pk_mul_f32 v[6:7], v[6:7], v[12:13]
	global_store_dwordx2 v[102:103], v[94:95], off
	v_pk_mul_f32 v[2:3], v[2:3], v[6:7]
	v_pk_mul_f32 v[6:7], v[8:9], v[14:15]
	v_cvt_pk_bf16_f32 v2, v2, v3
	v_pk_mul_f32 v[4:5], v[4:5], v[6:7]
	global_store_dwordx2 v[86:87], v[74:75], off
	v_cvt_pk_bf16_f32 v3, v4, v5
	global_store_dwordx2 v[70:71], v[58:59], off
	global_store_dwordx2 v[54:55], v[42:43], off
	global_store_dwordx2 v[38:39], v[26:27], off
	global_store_dwordx2 v[22:23], v[10:11], off
	global_store_dwordx2 v[22:23], v[2:3], off offset:32
	s_cbranch_scc0 .LBB0_749
